# RS prologue loop split over 8 waves with 16 loads in flight; ff1 and GEMM1 epilogue rstd loads hoisted; DA attention LDS reads pipelined
# baseline (speedup 1.0000x reference)
; __global__ void __launch_bounds__(512, 2) mk_fwd(Args a) {
;     ...
;             pg8::StaticOrder S; S.init(J.g.M, J.g.N, Gj, cj, 0);
;             if (J.SS == RS && !(l == 0 && sub == 0)) {
;                 pg8::Unit fu;
;                 for (int i = 0; S.next(i, fu); ++i) if (tid < 256) { const int row = (J.kind == 2 ? fu.pn : fu.pm) * 256 + tid;
;                     const f32x4* p = (const f32x4*)(SS + (size_t)row * 16); const f32x4 q0 = p[0], q1 = p[1], q2 = p[2], q3 = p[3];
;                     const float sm = (((q0.x + q0.y) + (q0.z + q0.w)) + ((q1.x + q1.y) + (q1.z + q1.w))) + (((q2.x + q2.y) + (q2.z + q2.w)) + ((q3.x + q3.y) + (q3.z + q3.w)));
;                     RS[row] = rsqrtf(sm * (1.f / 1024.f) + EPS); }
.LBB0_409:
	s_cmp_lg_u64 s[86:87], s[66:67]
	s_cselect_b64 s[2:3], -1, 0
	s_or_b64 s[2:3], s[2:3], s[44:45]
	s_mul_i32 s96, s11, s8
	s_and_b64 vcc, exec, s[2:3]
	s_cbranch_vccnz .LBB0_423
	s_lshl_b32 s2, s11, 3
	s_abs_i32 s3, s2
	v_cvt_f32_u32_e32 v0, s3
	s_sub_i32 s15, 0, s3
	s_ashr_i32 s77, s76, 31
	s_lshr_b32 s10, s96, 3
	v_rcp_iflag_f32_e32 v0, v0
	s_ashr_i32 s9, s25, 31
	s_mov_b32 s97, s17
	s_and_b32 s12, s96, 7
	v_mul_f32_e32 v0, 0x4f7ffffe, v0
	v_cvt_u32_f32_e32 v0, v0
	s_bfe_i32 s13, s11, 0x1001c
	s_add_i32 s14, s10, 1
	s_mov_b64 s[20:21], s[76:77]
	v_readfirstlane_b32 s16, v0
	s_mul_i32 s15, s15, s16
	s_mul_hi_u32 s15, s16, s15
	s_add_i32 s15, s16, s15
	v_readfirstlane_b32 s16, v235
	s_nop 1
	s_lshr_b32 s16, s16, 6
	s_mul_i32 s16, s16, s25
	s_add_u32 s20, s20, s16
	s_addc_u32 s21, s21, 0
	s_branch .LBB0_413
.LBB0_411:
	s_or_b64 exec, exec, s[22:23]
	s_lshl_b32 s16, s25, 3
	s_add_u32 s20, s20, s16
	s_addc_u32 s21, s21, 0
	s_mov_b64 s[22:23], 0

; __global__ void __launch_bounds__(512, 2) mk_fwd(Args a) {
;     ...
;                 for (int i = 0; S.next(i, fu); ++i) if (tid < 256) { const int row = (J.kind == 2 ? fu.pn : fu.pm) * 256 + tid;
;                     const f32x4* p = (const f32x4*)(SS + (size_t)row * 16); const f32x4 q0 = p[0], q1 = p[1], q2 = p[2], q3 = p[3];
;                     const float sm = (((q0.x + q0.y) + (q0.z + q0.w)) + ((q1.x + q1.y) + (q1.z + q1.w))) + (((q2.x + q2.y) + (q2.z + q2.w)) + ((q3.x + q3.y) + (q3.z + q3.w)));
;                     RS[row] = rsqrtf(sm * (1.f / 1024.f) + EPS); }
.LBB0_419:
	v_mov_b64_e32 v[2:3], s[96:97]
	v_cmp_lt_i64_e32 vcc, s[20:21], v[2:3]
	s_mov_b64 s[22:23], -1
	s_cbranch_vccz .LBB0_412
	s_mov_b64 s[22:23], exec
	s_and_b64 s[18:19], s[0:1], exec
	s_cselect_b32 s16, s58, s59
	v_and_b32_e32 v18, 63, v235
	v_lshl_add_u32 v18, s16, 8, v18
	v_add_u32_e32 v52, 64, v18
	v_add_u32_e32 v72, 128, v18
	v_add_u32_e32 v212, 192, v18
	v_ashrrev_i32_e32 v19, 31, v18
	v_lshlrev_b64 v[2:3], 6, v[18:19]
	v_lshl_add_u64 v[14:15], s[62:63], 0, v[2:3]
	v_ashrrev_i32_e32 v53, 31, v52
	v_lshlrev_b64 v[36:37], 6, v[52:53]
	v_lshl_add_u64 v[48:49], s[62:63], 0, v[36:37]
	v_ashrrev_i32_e32 v73, 31, v72
	v_lshlrev_b64 v[56:57], 6, v[72:73]
	v_lshl_add_u64 v[68:69], s[62:63], 0, v[56:57]
	v_ashrrev_i32_e32 v213, 31, v212
	v_lshlrev_b64 v[196:197], 6, v[212:213]
	v_lshl_add_u64 v[208:209], s[62:63], 0, v[196:197]
	global_load_dwordx4 v[2:5], v[14:15], off
	global_load_dwordx4 v[6:9], v[14:15], off offset:32
	global_load_dwordx4 v[10:13], v[14:15], off offset:16
	global_load_dwordx4 v[14:17], v[14:15], off offset:48
	global_load_dwordx4 v[36:39], v[48:49], off
	global_load_dwordx4 v[40:43], v[48:49], off offset:32
	global_load_dwordx4 v[44:47], v[48:49], off offset:16
	global_load_dwordx4 v[48:51], v[48:49], off offset:48
	global_load_dwordx4 v[56:59], v[68:69], off
	global_load_dwordx4 v[60:63], v[68:69], off offset:32
	global_load_dwordx4 v[64:67], v[68:69], off offset:16
	global_load_dwordx4 v[68:71], v[68:69], off offset:48
	global_load_dwordx4 v[196:199], v[208:209], off
	global_load_dwordx4 v[200:203], v[208:209], off offset:32
	global_load_dwordx4 v[204:207], v[208:209], off offset:16
	global_load_dwordx4 v[208:211], v[208:209], off offset:48
	s_waitcnt vmcnt(0)
	v_mov_b32_e32 v20, v2
	v_mov_b32_e32 v21, v6
	v_mov_b32_e32 v6, v3
	v_mov_b32_e32 v2, v4
	v_mov_b32_e32 v3, v8
	v_mov_b32_e32 v8, v5
	v_mov_b32_e32 v4, v10
	v_mov_b32_e32 v5, v14
	v_mov_b32_e32 v14, v11
	v_mov_b32_e32 v10, v12
	v_mov_b32_e32 v11, v16
	v_mov_b32_e32 v16, v13
	v_pk_add_f32 v[6:7], v[20:21], v[6:7]
	v_pk_add_f32 v[2:3], v[2:3], v[8:9]
	v_pk_add_f32 v[4:5], v[4:5], v[14:15]
	v_pk_add_f32 v[8:9], v[10:11], v[16:17]
	v_pk_add_f32 v[2:3], v[6:7], v[2:3]
	v_pk_add_f32 v[4:5], v[4:5], v[8:9]
	s_nop 0
	v_pk_add_f32 v[2:3], v[2:3], v[4:5]
	s_nop 0
	v_add_f32_e32 v0, v2, v3
	v_fmamk_f32 v0, v0, 0x3a800000, v228
	v_mul_f32_e32 v2, 0x4b800000, v0
	v_cmp_gt_f32_e32 vcc, s52, v0
	s_nop 1
	v_cndmask_b32_e32 v0, v0, v2, vcc
	v_rsq_f32_e32 v0, v0
	s_nop 0
	v_mul_f32_e32 v2, 0x45800000, v0
	v_cndmask_b32_e32 v0, v0, v2, vcc
	v_lshl_add_u64 v[2:3], v[18:19], 2, s[66:67]
	global_store_dword v[2:3], v0, off
	v_mov_b32_e32 v54, v36
	v_mov_b32_e32 v55, v40
	v_mov_b32_e32 v40, v37
	v_mov_b32_e32 v36, v38
	v_mov_b32_e32 v37, v42
	v_mov_b32_e32 v42, v39
	v_mov_b32_e32 v38, v44
	v_mov_b32_e32 v39, v48
	v_mov_b32_e32 v48, v45
	v_mov_b32_e32 v44, v46
	v_mov_b32_e32 v45, v50
	v_mov_b32_e32 v50, v47
	v_pk_add_f32 v[40:41], v[54:55], v[40:41]
	v_pk_add_f32 v[36:37], v[36:37], v[42:43]
	v_pk_add_f32 v[38:39], v[38:39], v[48:49]
	v_pk_add_f32 v[42:43], v[44:45], v[50:51]
	v_pk_add_f32 v[36:37], v[40:41], v[36:37]
	v_pk_add_f32 v[38:39], v[38:39], v[42:43]
	s_nop 0
	v_pk_add_f32 v[36:37], v[36:37], v[38:39]
	s_nop 0
	v_add_f32_e32 v216, v36, v37
	v_fmamk_f32 v216, v216, 0x3a800000, v228
	v_mul_f32_e32 v36, 0x4b800000, v216
	v_cmp_gt_f32_e32 vcc, s52, v216
	s_nop 1
	v_cndmask_b32_e32 v216, v216, v36, vcc
	v_rsq_f32_e32 v216, v216
	s_nop 0
	v_mul_f32_e32 v36, 0x45800000, v216
	v_cndmask_b32_e32 v216, v216, v36, vcc
	v_lshl_add_u64 v[36:37], v[52:53], 2, s[66:67]
	global_store_dword v[36:37], v216, off
	v_mov_b32_e32 v74, v56
	v_mov_b32_e32 v75, v60
	v_mov_b32_e32 v60, v57
	v_mov_b32_e32 v56, v58
	v_mov_b32_e32 v57, v62
	v_mov_b32_e32 v62, v59
	v_mov_b32_e32 v58, v64
	v_mov_b32_e32 v59, v68
	v_mov_b32_e32 v68, v65
	v_mov_b32_e32 v64, v66
	v_mov_b32_e32 v65, v70
	v_mov_b32_e32 v70, v67
	v_pk_add_f32 v[60:61], v[74:75], v[60:61]
	v_pk_add_f32 v[56:57], v[56:57], v[62:63]
	v_pk_add_f32 v[58:59], v[58:59], v[68:69]
	v_pk_add_f32 v[62:63], v[64:65], v[70:71]
	v_pk_add_f32 v[56:57], v[60:61], v[56:57]
	v_pk_add_f32 v[58:59], v[58:59], v[62:63]
	s_nop 0
	v_pk_add_f32 v[56:57], v[56:57], v[58:59]
	s_nop 0
	v_add_f32_e32 v217, v56, v57
	v_fmamk_f32 v217, v217, 0x3a800000, v228
	v_mul_f32_e32 v56, 0x4b800000, v217
	v_cmp_gt_f32_e32 vcc, s52, v217
	s_nop 1
	v_cndmask_b32_e32 v217, v217, v56, vcc
	v_rsq_f32_e32 v217, v217
	s_nop 0
	v_mul_f32_e32 v56, 0x45800000, v217
	v_cndmask_b32_e32 v217, v217, v56, vcc
	v_lshl_add_u64 v[56:57], v[72:73], 2, s[66:67]
	global_store_dword v[56:57], v217, off
	v_mov_b32_e32 v214, v196
	v_mov_b32_e32 v215, v200
	v_mov_b32_e32 v200, v197
	v_mov_b32_e32 v196, v198
	v_mov_b32_e32 v197, v202
	v_mov_b32_e32 v202, v199
	v_mov_b32_e32 v198, v204
	v_mov_b32_e32 v199, v208
	v_mov_b32_e32 v208, v205
	v_mov_b32_e32 v204, v206
	v_mov_b32_e32 v205, v210
	v_mov_b32_e32 v210, v207
	v_pk_add_f32 v[200:201], v[214:215], v[200:201]
	v_pk_add_f32 v[196:197], v[196:197], v[202:203]
	v_pk_add_f32 v[198:199], v[198:199], v[208:209]
	v_pk_add_f32 v[202:203], v[204:205], v[210:211]
	v_pk_add_f32 v[196:197], v[200:201], v[196:197]
	v_pk_add_f32 v[198:199], v[198:199], v[202:203]
	s_nop 0
	v_pk_add_f32 v[196:197], v[196:197], v[198:199]
	s_nop 0
	v_add_f32_e32 v218, v196, v197
	v_fmamk_f32 v218, v218, 0x3a800000, v228
	v_mul_f32_e32 v196, 0x4b800000, v218
	v_cmp_gt_f32_e32 vcc, s52, v218
	s_nop 1
	v_cndmask_b32_e32 v218, v218, v196, vcc
	v_rsq_f32_e32 v218, v218
	s_nop 0
	v_mul_f32_e32 v196, 0x45800000, v218
	v_cndmask_b32_e32 v218, v218, v196, vcc
	v_lshl_add_u64 v[196:197], v[212:213], 2, s[66:67]
	global_store_dword v[196:197], v218, off
	s_branch .LBB0_411

; DI unsigned cvtpk(float lo, float hi) { f32x2_t v = {lo, hi}; bf16x2_t b = __builtin_convertvector(v, bf16x2_t); return __builtin_bit_cast(unsigned, b); }
; DI float shx(float v, int mask, int lane) { return __builtin_bit_cast(float, __builtin_amdgcn_ds_bpermute((lane ^ mask) << 2, __builtin_bit_cast(int, v))); }
;     DI void operator()(const f32x4 (&acc)[2][2][4][2], const Unit& u, int wr, int wc, int fr, int fq) const {
;     ...
;         const float* gg = (u.pn < 2) ? gq : gk; const float ex = (u.pn < 2) ? QS64 : 1.f;
;         const int row0 = u.pm * BM + wr * 64 + fr, ln = fr + 16 * fq;
;         f32x4 g[2][2];
; #pragma unroll
;         for (int bj = 0; bj < 2; ++bj) { g[bj][0] = *(const f32x4*)(gg + 32 * bj + 8 * fq); g[bj][1] = *(const f32x4*)(gg + 32 * bj + 8 * fq + 4); }
; #pragma unroll
;         for (int ai = 0; ai < 2; ++ai)
; #pragma unroll
;             for (int m = 0; m < 4; ++m) { const int row = row0 + ai * HALF + m * 16; const float sc = SS[row];
;                 f32x4 v[2][2]; float ss = 0.f;
; #pragma unroll
;                 for (int bj = 0; bj < 2; ++bj)
; #pragma unroll
;                     for (int n = 0; n < 2; ++n) { v[bj][n] = acc[ai][bj][m][n] * sc; ss += (v[bj][n][0] * v[bj][n][0] + v[bj][n][1] * v[bj][n][1]) + (v[bj][n][2] * v[bj][n][2] + v[bj][n][3] * v[bj][n][3]); }
;                 ss += shx(ss, 16, ln); ss += shx(ss, 32, ln);
;                 const float rs = rsqrtf(ss * (1.f / 64.f) + EPS) * ex;
;                 bf16_t* rowp = O + (size_t)row * ldc + u.pn * BM + wc * 64 + 8 * fq;
; #pragma unroll
;                 for (int bj = 0; bj < 2; ++bj) { const f32x4 a0 = v[bj][0] * rs * g[bj][0], a1 = v[bj][1] * rs * g[bj][1];
;                     u32x4 w; w.x = cvtpk(a0[0], a0[1]); w.y = cvtpk(a0[2], a0[3]); w.z = cvtpk(a1[0], a1[1]); w.w = cvtpk(a1[2], a1[3]);
;                     __builtin_nontemporal_store(w, (u32x4*)(rowp + bj * 32)); }
;                 asm volatile("" ::: "memory"); }
.LBB0_456:
	s_and_b64 vcc, exec, s[48:49]
	s_cbranch_vccz .LBB0_525
	s_cmp_lt_i32 s65, 4
	s_mov_b64 s[48:49], -1
	s_cbranch_scc0 .LBB0_459
	s_cmp_lt_i32 s65, 2
	s_cselect_b64 vcc, -1, 0
	s_and_b64 s[2:3], vcc, exec
	v_lshlrev_b32_e32 v176, 3, v236
	v_lshl_add_u32 v148, s64, 8, v237
	s_cselect_b32 s3, s79, s81
	s_cselect_b32 s2, s78, s80
	v_lshlrev_b32_e32 v0, 2, v176
	v_ashrrev_i32_e32 v149, 31, v148
	v_lshl_add_u64 v[130:131], s[2:3], 0, v[0:1]
	v_mov_b32_e32 v0, 0x3e38aa3b
	v_lshl_add_u64 v[146:147], v[148:149], 2, s[86:87]
	flat_load_dwordx4 v[142:145], v[130:131]
	flat_load_dwordx4 v[138:141], v[130:131] offset:16
	flat_load_dwordx4 v[134:137], v[130:131] offset:128
	s_nop 0
	flat_load_dwordx4 v[130:133], v[130:131] offset:144
	v_cndmask_b32_e32 v170, 1.0, v0, vcc
	global_load_dword v0, v[146:147], off
	global_load_dword v177, v[146:147], off offset:64
	global_load_dword v178, v[146:147], off offset:128
	global_load_dword v179, v[146:147], off offset:192
	global_load_dword v180, v[146:147], off offset:512
	global_load_dword v181, v[146:147], off offset:576
	global_load_dword v182, v[146:147], off offset:640
	global_load_dword v183, v[146:147], off offset:704
	v_mul_lo_u32 v149, s82, v149
	s_mov_b32 s29, s17
	v_or_b32_e32 v171, 16, v148
	s_waitcnt vmcnt(0) lgkmcnt(0)
	v_pk_mul_f32 v[164:165], v[126:127], v[0:1] op_sel_hi:[1,0]
	v_pk_mul_f32 v[166:167], v[128:129], v[0:1] op_sel_hi:[1,0]
	v_pk_mul_f32 v[152:153], v[164:165], v[164:165]
	v_pk_mul_f32 v[150:151], v[166:167], v[166:167]
	v_pk_mul_f32 v[160:161], v[122:123], v[0:1] op_sel_hi:[1,0]
	v_pk_mov_b32 v[154:155], v[152:153], v[150:151] op_sel:[1,0]
	v_mov_b32_e32 v153, v151
	v_pk_add_f32 v[150:151], v[154:155], v[152:153]
	v_pk_mul_f32 v[162:163], v[124:125], v[0:1] op_sel_hi:[1,0]
	v_pk_add_f32 v[158:159], v[150:151], v[150:151] op_sel_hi:[0,1]
	v_pk_mul_f32 v[150:151], v[162:163], v[162:163]
	v_pk_mul_f32 v[152:153], v[160:161], v[160:161]
	v_pk_mul_f32 v[156:157], v[118:119], v[0:1] op_sel_hi:[1,0]
	v_pk_mov_b32 v[154:155], v[152:153], v[150:151] op_sel:[1,0]
	v_mov_b32_e32 v153, v151
	v_pk_add_f32 v[150:151], v[154:155], v[152:153]
	v_pk_mul_f32 v[154:155], v[120:121], v[0:1] op_sel_hi:[1,0]
	v_pk_add_f32 v[168:169], v[150:151], v[150:151] op_sel_hi:[0,1]
	v_mul_f32_e32 v150, v156, v156
	v_pk_fma_f32 v[172:173], v[156:157], v[156:157], v[150:151] op_sel_hi:[1,1,0]
	v_mul_f32_e32 v150, v154, v154
	v_pk_fma_f32 v[174:175], v[154:155], v[154:155], v[150:151] op_sel_hi:[1,1,0]
	v_pk_mul_f32 v[150:151], v[116:117], v[0:1] op_sel_hi:[1,0]
	v_pk_mul_f32 v[152:153], v[114:115], v[0:1] op_sel_hi:[1,0]
	v_mul_f32_e32 v158, v150, v150
	v_mul_f32_e32 v172, v152, v152
	v_mul_f32_e32 v174, v153, v153
	v_mul_f32_e32 v168, v151, v151
	v_pk_add_f32 v[172:173], v[172:173], v[174:175]
	v_pk_add_f32 v[158:159], v[158:159], v[168:169]
	v_mad_u64_u32 v[168:169], s[2:3], s82, v148, 0
	v_pk_add_f32 v[158:159], v[172:173], v[158:159]
	s_lshl_b32 s2, s65, 8
	v_add_f32_e32 v0, v158, v159
	ds_bpermute_b32 v158, v239, v0
	s_ashr_i32 s3, s2, 31
	s_lshl_b64 s[48:49], s[2:3], 1
	s_waitcnt lgkmcnt(0)
	v_add_f32_e32 v0, v0, v158
	ds_bpermute_b32 v158, v240, v0
	s_waitcnt lgkmcnt(0)
	v_add_f32_e32 v0, v0, v158
	v_fmamk_f32 v0, v0, 0x3c800000, v228
	v_cmp_gt_f32_e32 vcc, s52, v0
	v_mul_f32_e32 v158, 0x4b800000, v0
	s_nop 0
	v_cndmask_b32_e32 v0, v0, v158, vcc
	v_rsq_f32_e32 v0, v0
	s_nop 0
	v_mul_f32_e32 v158, 0x45800000, v0
	v_cndmask_b32_e32 v0, v0, v158, vcc
	v_mul_f32_e32 v158, v170, v0
	v_mul_lo_u32 v0, s83, v148
	v_add3_u32 v169, v169, v149, v0
	v_lshl_add_u64 v[168:169], v[168:169], 1, s[84:85]
	v_lshl_add_u64 v[168:169], v[168:169], 0, s[48:49]
	v_pk_mul_f32 v[164:165], v[164:165], v[158:159] op_sel_hi:[1,0]
	v_pk_mul_f32 v[166:167], v[166:167], v[158:159] op_sel_hi:[1,0]
	v_pk_mul_f32 v[160:161], v[160:161], v[158:159] op_sel_hi:[1,0]
	v_pk_mul_f32 v[162:163], v[162:163], v[158:159] op_sel_hi:[1,0]
	v_pk_mul_f32 v[156:157], v[156:157], v[158:159] op_sel_hi:[1,0]
	v_pk_mul_f32 v[154:155], v[154:155], v[158:159] op_sel_hi:[1,0]
	v_pk_mul_f32 v[152:153], v[152:153], v[158:159] op_sel_hi:[1,0]
	v_pk_mul_f32 v[150:151], v[150:151], v[158:159] op_sel_hi:[1,0]
	v_lshl_add_u64 v[168:169], v[168:169], 0, s[28:29]
	v_lshlrev_b32_e32 v0, 1, v176
	v_pk_mul_f32 v[166:167], v[144:145], v[166:167]
	v_pk_mul_f32 v[164:165], v[142:143], v[164:165]
	v_pk_mul_f32 v[172:173], v[140:141], v[162:163]
	v_pk_mul_f32 v[162:163], v[138:139], v[160:161]
	v_pk_mul_f32 v[154:155], v[136:137], v[154:155]
	v_pk_mul_f32 v[156:157], v[134:135], v[156:157]
	v_pk_mul_f32 v[158:159], v[132:133], v[150:151]
	v_pk_mul_f32 v[152:153], v[130:131], v[152:153]
	v_lshl_add_u64 v[168:169], v[168:169], 0, v[0:1]
	v_cvt_pk_bf16_f32 v160, v164, v165
	v_cvt_pk_bf16_f32 v161, v166, v167
	v_cvt_pk_bf16_f32 v162, v162, v163
	v_cvt_pk_bf16_f32 v163, v172, v173
	v_cvt_pk_bf16_f32 v150, v156, v157
	v_cvt_pk_bf16_f32 v151, v154, v155
	v_cvt_pk_bf16_f32 v152, v152, v153
	v_cvt_pk_bf16_f32 v153, v158, v159
	flat_store_dwordx4 v[168:169], v[160:163] nt
	flat_store_dwordx4 v[168:169], v[150:153] offset:64 nt
	v_mov_b32_e32 v164, v177
	v_pk_mul_f32 v[160:161], v[108:109], v[164:165] op_sel_hi:[1,0]
	v_pk_mul_f32 v[150:151], v[110:111], v[164:165] op_sel_hi:[1,0]
	v_pk_mul_f32 v[152:153], v[112:113], v[164:165] op_sel_hi:[1,0]
	v_pk_mul_f32 v[156:157], v[150:151], v[150:151]
	v_pk_mul_f32 v[154:155], v[152:153], v[152:153]
	s_nop 0
	v_pk_mov_b32 v[158:159], v[156:157], v[154:155] op_sel:[1,0]
	v_mov_b32_e32 v157, v155
	v_pk_add_f32 v[154:155], v[158:159], v[156:157]
	v_pk_mul_f32 v[158:159], v[106:107], v[164:165] op_sel_hi:[1,0]
	v_pk_add_f32 v[166:167], v[154:155], v[154:155] op_sel_hi:[0,1]
	v_pk_mul_f32 v[154:155], v[160:161], v[160:161]
	v_pk_mul_f32 v[156:157], v[158:159], v[158:159]
	s_nop 0
	v_pk_mov_b32 v[162:163], v[156:157], v[154:155] op_sel:[1,0]
	v_mov_b32_e32 v157, v155
	v_pk_add_f32 v[154:155], v[162:163], v[156:157]
	v_pk_mul_f32 v[156:157], v[102:103], v[164:165] op_sel_hi:[1,0]
	v_pk_add_f32 v[168:169], v[154:155], v[154:155] op_sel_hi:[0,1]
	v_pk_mul_f32 v[154:155], v[104:105], v[164:165] op_sel_hi:[1,0]
	v_mul_f32_e32 v162, v156, v156
	v_pk_fma_f32 v[172:173], v[156:157], v[156:157], v[162:163] op_sel_hi:[1,1,0]
	v_mul_f32_e32 v162, v154, v154
	v_pk_fma_f32 v[174:175], v[154:155], v[154:155], v[162:163] op_sel_hi:[1,1,0]
	v_pk_mul_f32 v[162:163], v[100:101], v[164:165] op_sel_hi:[1,0]
	v_pk_mul_f32 v[164:165], v[98:99], v[164:165] op_sel_hi:[1,0]
	v_mul_f32_e32 v166, v162, v162
	v_mul_f32_e32 v172, v164, v164
	v_mul_f32_e32 v174, v165, v165
	v_mul_f32_e32 v168, v163, v163
	v_pk_add_f32 v[172:173], v[172:173], v[174:175]
	v_pk_add_f32 v[166:167], v[166:167], v[168:169]
	v_mad_u64_u32 v[168:169], s[2:3], s82, v171, 0
	v_pk_add_f32 v[166:167], v[172:173], v[166:167]
	s_nop 0
	v_add_f32_e32 v166, v166, v167
	ds_bpermute_b32 v167, v239, v166
	s_waitcnt lgkmcnt(0)
; DI unsigned cvtpk(float lo, float hi) { f32x2_t v = {lo, hi}; bf16x2_t b = __builtin_convertvector(v, bf16x2_t); return __builtin_bit_cast(unsigned, b); }
; DI float shx(float v, int mask, int lane) { return __builtin_bit_cast(float, __builtin_amdgcn_ds_bpermute((lane ^ mask) << 2, __builtin_bit_cast(int, v))); }
;     DI void operator()(const f32x4 (&acc)[2][2][4][2], const Unit& u, int wr, int wc, int fr, int fq) const {
;     ...
;             for (int m = 0; m < 4; ++m) { const int row = row0 + ai * HALF + m * 16; const float sc = SS[row];
;                 f32x4 v[2][2]; float ss = 0.f;
; #pragma unroll
;                 for (int bj = 0; bj < 2; ++bj)
; #pragma unroll
;                     for (int n = 0; n < 2; ++n) { v[bj][n] = acc[ai][bj][m][n] * sc; ss += (v[bj][n][0] * v[bj][n][0] + v[bj][n][1] * v[bj][n][1]) + (v[bj][n][2] * v[bj][n][2] + v[bj][n][3] * v[bj][n][3]); }
;                 ss += shx(ss, 16, ln); ss += shx(ss, 32, ln);
;                 const float rs = rsqrtf(ss * (1.f / 64.f) + EPS) * ex;
;                 bf16_t* rowp = O + (size_t)row * ldc + u.pn * BM + wc * 64 + 8 * fq;
; #pragma unroll
;                 for (int bj = 0; bj < 2; ++bj) { const f32x4 a0 = v[bj][0] * rs * g[bj][0], a1 = v[bj][1] * rs * g[bj][1];
;                     u32x4 w; w.x = cvtpk(a0[0], a0[1]); w.y = cvtpk(a0[2], a0[3]); w.z = cvtpk(a1[0], a1[1]); w.w = cvtpk(a1[2], a1[3]);
;                     __builtin_nontemporal_store(w, (u32x4*)(rowp + bj * 32)); }
;                 asm volatile("" ::: "memory"); }
	v_add_f32_e32 v166, v166, v167
	ds_bpermute_b32 v167, v240, v166
	s_waitcnt lgkmcnt(0)
	v_add_f32_e32 v166, v166, v167
	v_fmamk_f32 v166, v166, 0x3c800000, v228
	v_cmp_gt_f32_e32 vcc, s52, v166
	v_mul_f32_e32 v167, 0x4b800000, v166
	s_nop 0
	v_cndmask_b32_e32 v166, v166, v167, vcc
	v_rsq_f32_e32 v166, v166
	s_nop 0
	v_mul_f32_e32 v167, 0x45800000, v166
	v_cndmask_b32_e32 v166, v166, v167, vcc
	v_mul_lo_u32 v167, s83, v171
	v_add3_u32 v169, v169, v149, v167
	v_mul_f32_e32 v166, v170, v166
	v_lshl_add_u64 v[168:169], v[168:169], 1, s[84:85]
	v_lshl_add_u64 v[168:169], v[168:169], 0, s[48:49]
	v_pk_mul_f32 v[150:151], v[150:151], v[166:167] op_sel_hi:[1,0]
	v_pk_mul_f32 v[152:153], v[152:153], v[166:167] op_sel_hi:[1,0]
	v_pk_mul_f32 v[158:159], v[158:159], v[166:167] op_sel_hi:[1,0]
	v_pk_mul_f32 v[160:161], v[160:161], v[166:167] op_sel_hi:[1,0]
	v_lshl_add_u64 v[168:169], v[168:169], 0, s[28:29]
	v_pk_mul_f32 v[152:153], v[144:145], v[152:153]
	v_pk_mul_f32 v[150:151], v[142:143], v[150:151]
	v_pk_mul_f32 v[160:161], v[140:141], v[160:161]
	v_pk_mul_f32 v[158:159], v[138:139], v[158:159]
	v_lshl_add_u64 v[168:169], v[168:169], 0, v[0:1]
	v_cvt_pk_bf16_f32 v150, v150, v151
	v_cvt_pk_bf16_f32 v151, v152, v153
	v_cvt_pk_bf16_f32 v152, v158, v159
	v_cvt_pk_bf16_f32 v153, v160, v161
	flat_store_dwordx4 v[168:169], v[150:153] nt
	v_or_b32_e32 v171, 32, v148
	s_nop 0
	v_pk_mul_f32 v[150:151], v[156:157], v[166:167] op_sel_hi:[1,0]
	v_pk_mul_f32 v[152:153], v[154:155], v[166:167] op_sel_hi:[1,0]
	v_pk_mul_f32 v[154:155], v[164:165], v[166:167] op_sel_hi:[1,0]
	v_pk_mul_f32 v[156:157], v[162:163], v[166:167] op_sel_hi:[1,0]
	v_pk_mul_f32 v[152:153], v[136:137], v[152:153]
	v_pk_mul_f32 v[150:151], v[134:135], v[150:151]
	v_pk_mul_f32 v[156:157], v[132:133], v[156:157]
	v_pk_mul_f32 v[154:155], v[130:131], v[154:155]
	v_cvt_pk_bf16_f32 v150, v150, v151
	v_cvt_pk_bf16_f32 v151, v152, v153
	v_cvt_pk_bf16_f32 v152, v154, v155
	v_cvt_pk_bf16_f32 v153, v156, v157
	flat_store_dwordx4 v[168:169], v[150:153] offset:64 nt
	v_mov_b32_e32 v164, v178
	v_pk_mul_f32 v[160:161], v[92:93], v[164:165] op_sel_hi:[1,0]
	v_pk_mul_f32 v[150:151], v[94:95], v[164:165] op_sel_hi:[1,0]
	v_pk_mul_f32 v[152:153], v[96:97], v[164:165] op_sel_hi:[1,0]
	v_pk_mul_f32 v[156:157], v[150:151], v[150:151]
	v_pk_mul_f32 v[154:155], v[152:153], v[152:153]
	s_nop 0
	v_pk_mov_b32 v[158:159], v[156:157], v[154:155] op_sel:[1,0]
	v_mov_b32_e32 v157, v155
	v_pk_add_f32 v[154:155], v[158:159], v[156:157]
	v_pk_mul_f32 v[158:159], v[90:91], v[164:165] op_sel_hi:[1,0]
	v_pk_add_f32 v[166:167], v[154:155], v[154:155] op_sel_hi:[0,1]
	v_pk_mul_f32 v[154:155], v[160:161], v[160:161]
	v_pk_mul_f32 v[156:157], v[158:159], v[158:159]
	s_nop 0
	v_pk_mov_b32 v[162:163], v[156:157], v[154:155] op_sel:[1,0]
	v_mov_b32_e32 v157, v155
	v_pk_add_f32 v[154:155], v[162:163], v[156:157]
	v_pk_mul_f32 v[156:157], v[86:87], v[164:165] op_sel_hi:[1,0]
	v_pk_add_f32 v[168:169], v[154:155], v[154:155] op_sel_hi:[0,1]
	v_pk_mul_f32 v[154:155], v[88:89], v[164:165] op_sel_hi:[1,0]
	v_mul_f32_e32 v162, v156, v156
	v_pk_fma_f32 v[172:173], v[156:157], v[156:157], v[162:163] op_sel_hi:[1,1,0]
	v_mul_f32_e32 v162, v154, v154
	v_pk_fma_f32 v[174:175], v[154:155], v[154:155], v[162:163] op_sel_hi:[1,1,0]
	v_pk_mul_f32 v[162:163], v[84:85], v[164:165] op_sel_hi:[1,0]
	v_pk_mul_f32 v[164:165], v[82:83], v[164:165] op_sel_hi:[1,0]
	v_mul_f32_e32 v166, v162, v162
	v_mul_f32_e32 v172, v164, v164
	v_mul_f32_e32 v174, v165, v165
	v_mul_f32_e32 v168, v163, v163
	v_pk_add_f32 v[172:173], v[172:173], v[174:175]
	v_pk_add_f32 v[166:167], v[166:167], v[168:169]
	v_mad_u64_u32 v[168:169], s[2:3], s82, v171, 0
	v_pk_add_f32 v[166:167], v[172:173], v[166:167]
	s_nop 0
	v_add_f32_e32 v166, v166, v167
	ds_bpermute_b32 v167, v239, v166
	s_waitcnt lgkmcnt(0)
	v_add_f32_e32 v166, v166, v167
	ds_bpermute_b32 v167, v240, v166
	s_waitcnt lgkmcnt(0)
	v_add_f32_e32 v166, v166, v167
	v_fmamk_f32 v166, v166, 0x3c800000, v228
	v_cmp_gt_f32_e32 vcc, s52, v166
	v_mul_f32_e32 v167, 0x4b800000, v166
	s_nop 0
	v_cndmask_b32_e32 v166, v166, v167, vcc
	v_rsq_f32_e32 v166, v166
	s_nop 0
	v_mul_f32_e32 v167, 0x45800000, v166
	v_cndmask_b32_e32 v166, v166, v167, vcc
	v_mul_lo_u32 v167, s83, v171
	v_add3_u32 v169, v169, v149, v167
	v_mul_f32_e32 v166, v170, v166
	v_lshl_add_u64 v[168:169], v[168:169], 1, s[84:85]
	v_lshl_add_u64 v[168:169], v[168:169], 0, s[48:49]
	v_pk_mul_f32 v[150:151], v[150:151], v[166:167] op_sel_hi:[1,0]
	v_pk_mul_f32 v[152:153], v[152:153], v[166:167] op_sel_hi:[1,0]
	v_pk_mul_f32 v[158:159], v[158:159], v[166:167] op_sel_hi:[1,0]
	v_pk_mul_f32 v[160:161], v[160:161], v[166:167] op_sel_hi:[1,0]
	v_lshl_add_u64 v[168:169], v[168:169], 0, s[28:29]
	v_pk_mul_f32 v[152:153], v[144:145], v[152:153]
	v_pk_mul_f32 v[150:151], v[142:143], v[150:151]
	v_pk_mul_f32 v[160:161], v[140:141], v[160:161]
	v_pk_mul_f32 v[158:159], v[138:139], v[158:159]
	v_lshl_add_u64 v[168:169], v[168:169], 0, v[0:1]
	v_cvt_pk_bf16_f32 v150, v150, v151
	v_cvt_pk_bf16_f32 v151, v152, v153
	v_cvt_pk_bf16_f32 v152, v158, v159
	v_cvt_pk_bf16_f32 v153, v160, v161
	flat_store_dwordx4 v[168:169], v[150:153] nt
	v_or_b32_e32 v171, 48, v148
	s_nop 0
	v_pk_mul_f32 v[150:151], v[156:157], v[166:167] op_sel_hi:[1,0]
	v_pk_mul_f32 v[152:153], v[154:155], v[166:167] op_sel_hi:[1,0]
	v_pk_mul_f32 v[154:155], v[164:165], v[166:167] op_sel_hi:[1,0]
	v_pk_mul_f32 v[156:157], v[162:163], v[166:167] op_sel_hi:[1,0]
	v_pk_mul_f32 v[152:153], v[136:137], v[152:153]
	v_pk_mul_f32 v[150:151], v[134:135], v[150:151]
	v_pk_mul_f32 v[156:157], v[132:133], v[156:157]
; DI unsigned cvtpk(float lo, float hi) { f32x2_t v = {lo, hi}; bf16x2_t b = __builtin_convertvector(v, bf16x2_t); return __builtin_bit_cast(unsigned, b); }
; DI float shx(float v, int mask, int lane) { return __builtin_bit_cast(float, __builtin_amdgcn_ds_bpermute((lane ^ mask) << 2, __builtin_bit_cast(int, v))); }
;     DI void operator()(const f32x4 (&acc)[2][2][4][2], const Unit& u, int wr, int wc, int fr, int fq) const {
;     ...
;             for (int m = 0; m < 4; ++m) { const int row = row0 + ai * HALF + m * 16; const float sc = SS[row];
;                 f32x4 v[2][2]; float ss = 0.f;
; #pragma unroll
;                 for (int bj = 0; bj < 2; ++bj)
; #pragma unroll
;                     for (int n = 0; n < 2; ++n) { v[bj][n] = acc[ai][bj][m][n] * sc; ss += (v[bj][n][0] * v[bj][n][0] + v[bj][n][1] * v[bj][n][1]) + (v[bj][n][2] * v[bj][n][2] + v[bj][n][3] * v[bj][n][3]); }
;                 ss += shx(ss, 16, ln); ss += shx(ss, 32, ln);
;                 const float rs = rsqrtf(ss * (1.f / 64.f) + EPS) * ex;
;                 bf16_t* rowp = O + (size_t)row * ldc + u.pn * BM + wc * 64 + 8 * fq;
; #pragma unroll
;                 for (int bj = 0; bj < 2; ++bj) { const f32x4 a0 = v[bj][0] * rs * g[bj][0], a1 = v[bj][1] * rs * g[bj][1];
;                     u32x4 w; w.x = cvtpk(a0[0], a0[1]); w.y = cvtpk(a0[2], a0[3]); w.z = cvtpk(a1[0], a1[1]); w.w = cvtpk(a1[2], a1[3]);
;                     __builtin_nontemporal_store(w, (u32x4*)(rowp + bj * 32)); }
;                 asm volatile("" ::: "memory"); }
	v_pk_mul_f32 v[154:155], v[130:131], v[154:155]
	v_cvt_pk_bf16_f32 v150, v150, v151
	v_cvt_pk_bf16_f32 v151, v152, v153
	v_cvt_pk_bf16_f32 v152, v154, v155
	v_cvt_pk_bf16_f32 v153, v156, v157
	flat_store_dwordx4 v[168:169], v[150:153] offset:64 nt
	v_mov_b32_e32 v164, v179
	v_pk_mul_f32 v[160:161], v[76:77], v[164:165] op_sel_hi:[1,0]
	v_pk_mul_f32 v[150:151], v[78:79], v[164:165] op_sel_hi:[1,0]
	v_pk_mul_f32 v[152:153], v[80:81], v[164:165] op_sel_hi:[1,0]
	v_pk_mul_f32 v[156:157], v[150:151], v[150:151]
	v_pk_mul_f32 v[154:155], v[152:153], v[152:153]
	s_nop 0
	v_pk_mov_b32 v[158:159], v[156:157], v[154:155] op_sel:[1,0]
	v_mov_b32_e32 v157, v155
	v_pk_add_f32 v[154:155], v[158:159], v[156:157]
	v_pk_mul_f32 v[158:159], v[74:75], v[164:165] op_sel_hi:[1,0]
	v_pk_add_f32 v[166:167], v[154:155], v[154:155] op_sel_hi:[0,1]
	v_pk_mul_f32 v[154:155], v[160:161], v[160:161]
	v_pk_mul_f32 v[156:157], v[158:159], v[158:159]
	s_nop 0
	v_pk_mov_b32 v[162:163], v[156:157], v[154:155] op_sel:[1,0]
	v_mov_b32_e32 v157, v155
	v_pk_add_f32 v[154:155], v[162:163], v[156:157]
	v_pk_mul_f32 v[156:157], v[70:71], v[164:165] op_sel_hi:[1,0]
	v_pk_add_f32 v[168:169], v[154:155], v[154:155] op_sel_hi:[0,1]
	v_pk_mul_f32 v[154:155], v[72:73], v[164:165] op_sel_hi:[1,0]
	v_mul_f32_e32 v162, v156, v156
	v_pk_fma_f32 v[172:173], v[156:157], v[156:157], v[162:163] op_sel_hi:[1,1,0]
	v_mul_f32_e32 v162, v154, v154
	v_pk_fma_f32 v[174:175], v[154:155], v[154:155], v[162:163] op_sel_hi:[1,1,0]
	v_pk_mul_f32 v[162:163], v[68:69], v[164:165] op_sel_hi:[1,0]
	v_pk_mul_f32 v[164:165], v[66:67], v[164:165] op_sel_hi:[1,0]
	v_mul_f32_e32 v166, v162, v162
	v_mul_f32_e32 v172, v164, v164
	v_mul_f32_e32 v174, v165, v165
	v_mul_f32_e32 v168, v163, v163
	v_pk_add_f32 v[172:173], v[172:173], v[174:175]
	v_pk_add_f32 v[166:167], v[166:167], v[168:169]
	v_mad_u64_u32 v[168:169], s[2:3], s82, v171, 0
	v_pk_add_f32 v[166:167], v[172:173], v[166:167]
	s_nop 0
	v_add_f32_e32 v166, v166, v167
	ds_bpermute_b32 v167, v239, v166
	s_waitcnt lgkmcnt(0)
	v_add_f32_e32 v166, v166, v167
	ds_bpermute_b32 v167, v240, v166
	s_waitcnt lgkmcnt(0)
	v_add_f32_e32 v166, v166, v167
	v_fmamk_f32 v166, v166, 0x3c800000, v228
	v_cmp_gt_f32_e32 vcc, s52, v166
	v_mul_f32_e32 v167, 0x4b800000, v166
	s_nop 0
	v_cndmask_b32_e32 v166, v166, v167, vcc
	v_rsq_f32_e32 v166, v166
	s_nop 0
	v_mul_f32_e32 v167, 0x45800000, v166
	v_cndmask_b32_e32 v166, v166, v167, vcc
	v_mul_lo_u32 v167, s83, v171
	v_add3_u32 v169, v169, v149, v167
	v_mul_f32_e32 v166, v170, v166
	v_lshl_add_u64 v[168:169], v[168:169], 1, s[84:85]
	v_lshl_add_u64 v[168:169], v[168:169], 0, s[48:49]
	v_pk_mul_f32 v[150:151], v[150:151], v[166:167] op_sel_hi:[1,0]
	v_pk_mul_f32 v[152:153], v[152:153], v[166:167] op_sel_hi:[1,0]
	v_pk_mul_f32 v[158:159], v[158:159], v[166:167] op_sel_hi:[1,0]
	v_pk_mul_f32 v[160:161], v[160:161], v[166:167] op_sel_hi:[1,0]
	v_lshl_add_u64 v[168:169], v[168:169], 0, s[28:29]
	v_pk_mul_f32 v[152:153], v[144:145], v[152:153]
	v_pk_mul_f32 v[150:151], v[142:143], v[150:151]
	v_pk_mul_f32 v[160:161], v[140:141], v[160:161]
	v_pk_mul_f32 v[158:159], v[138:139], v[158:159]
	v_lshl_add_u64 v[168:169], v[168:169], 0, v[0:1]
	v_cvt_pk_bf16_f32 v150, v150, v151
	v_cvt_pk_bf16_f32 v151, v152, v153
	v_cvt_pk_bf16_f32 v152, v158, v159
	v_cvt_pk_bf16_f32 v153, v160, v161
	flat_store_dwordx4 v[168:169], v[150:153] nt
	v_add_u32_e32 v149, 0x80, v148
	v_ashrrev_i32_e32 v171, 31, v149
	v_pk_mul_f32 v[150:151], v[156:157], v[166:167] op_sel_hi:[1,0]
	v_pk_mul_f32 v[152:153], v[154:155], v[166:167] op_sel_hi:[1,0]
	v_pk_mul_f32 v[154:155], v[164:165], v[166:167] op_sel_hi:[1,0]
	v_pk_mul_f32 v[156:157], v[162:163], v[166:167] op_sel_hi:[1,0]
	v_pk_mul_f32 v[152:153], v[136:137], v[152:153]
	v_pk_mul_f32 v[150:151], v[134:135], v[150:151]
	v_pk_mul_f32 v[156:157], v[132:133], v[156:157]
	v_pk_mul_f32 v[154:155], v[130:131], v[154:155]
	v_cvt_pk_bf16_f32 v150, v150, v151
	v_cvt_pk_bf16_f32 v151, v152, v153
	v_cvt_pk_bf16_f32 v152, v154, v155
	v_cvt_pk_bf16_f32 v153, v156, v157
	flat_store_dwordx4 v[168:169], v[150:153] offset:64 nt
	v_mov_b32_e32 v164, v180
	v_pk_mul_f32 v[160:161], v[60:61], v[164:165] op_sel_hi:[1,0]
	v_pk_mul_f32 v[150:151], v[62:63], v[164:165] op_sel_hi:[1,0]
	v_pk_mul_f32 v[152:153], v[64:65], v[164:165] op_sel_hi:[1,0]
	v_pk_mul_f32 v[156:157], v[150:151], v[150:151]
	v_pk_mul_f32 v[154:155], v[152:153], v[152:153]
	s_nop 0
	v_pk_mov_b32 v[158:159], v[156:157], v[154:155] op_sel:[1,0]
	v_mov_b32_e32 v157, v155
	v_pk_add_f32 v[154:155], v[158:159], v[156:157]
	v_pk_mul_f32 v[158:159], v[58:59], v[164:165] op_sel_hi:[1,0]
	v_pk_add_f32 v[166:167], v[154:155], v[154:155] op_sel_hi:[0,1]
	v_pk_mul_f32 v[154:155], v[160:161], v[160:161]
	v_pk_mul_f32 v[156:157], v[158:159], v[158:159]
	s_nop 0
	v_pk_mov_b32 v[162:163], v[156:157], v[154:155] op_sel:[1,0]
	v_mov_b32_e32 v157, v155
	v_pk_add_f32 v[154:155], v[162:163], v[156:157]
	v_pk_mul_f32 v[156:157], v[54:55], v[164:165] op_sel_hi:[1,0]
	v_pk_add_f32 v[168:169], v[154:155], v[154:155] op_sel_hi:[0,1]
	v_pk_mul_f32 v[154:155], v[56:57], v[164:165] op_sel_hi:[1,0]
	v_mul_f32_e32 v162, v156, v156
	v_pk_fma_f32 v[172:173], v[156:157], v[156:157], v[162:163] op_sel_hi:[1,1,0]
	v_mul_f32_e32 v162, v154, v154
	v_pk_fma_f32 v[174:175], v[154:155], v[154:155], v[162:163] op_sel_hi:[1,1,0]
	v_pk_mul_f32 v[162:163], v[52:53], v[164:165] op_sel_hi:[1,0]
	v_pk_mul_f32 v[164:165], v[50:51], v[164:165] op_sel_hi:[1,0]
	v_mul_f32_e32 v166, v162, v162
	v_mul_f32_e32 v172, v164, v164
	v_mul_f32_e32 v174, v165, v165
	v_mul_f32_e32 v168, v163, v163
	v_pk_add_f32 v[172:173], v[172:173], v[174:175]
	v_pk_add_f32 v[166:167], v[166:167], v[168:169]
	v_mad_u64_u32 v[168:169], s[2:3], s82, v149, 0
	v_pk_add_f32 v[166:167], v[172:173], v[166:167]
	s_nop 0
	v_add_f32_e32 v166, v166, v167
	ds_bpermute_b32 v167, v239, v166
	s_waitcnt lgkmcnt(0)
; DI unsigned cvtpk(float lo, float hi) { f32x2_t v = {lo, hi}; bf16x2_t b = __builtin_convertvector(v, bf16x2_t); return __builtin_bit_cast(unsigned, b); }
; DI float shx(float v, int mask, int lane) { return __builtin_bit_cast(float, __builtin_amdgcn_ds_bpermute((lane ^ mask) << 2, __builtin_bit_cast(int, v))); }
;     DI void operator()(const f32x4 (&acc)[2][2][4][2], const Unit& u, int wr, int wc, int fr, int fq) const {
;     ...
;             for (int m = 0; m < 4; ++m) { const int row = row0 + ai * HALF + m * 16; const float sc = SS[row];
;                 f32x4 v[2][2]; float ss = 0.f;
; #pragma unroll
;                 for (int bj = 0; bj < 2; ++bj)
; #pragma unroll
;                     for (int n = 0; n < 2; ++n) { v[bj][n] = acc[ai][bj][m][n] * sc; ss += (v[bj][n][0] * v[bj][n][0] + v[bj][n][1] * v[bj][n][1]) + (v[bj][n][2] * v[bj][n][2] + v[bj][n][3] * v[bj][n][3]); }
;                 ss += shx(ss, 16, ln); ss += shx(ss, 32, ln);
;                 const float rs = rsqrtf(ss * (1.f / 64.f) + EPS) * ex;
;                 bf16_t* rowp = O + (size_t)row * ldc + u.pn * BM + wc * 64 + 8 * fq;
; #pragma unroll
;                 for (int bj = 0; bj < 2; ++bj) { const f32x4 a0 = v[bj][0] * rs * g[bj][0], a1 = v[bj][1] * rs * g[bj][1];
;                     u32x4 w; w.x = cvtpk(a0[0], a0[1]); w.y = cvtpk(a0[2], a0[3]); w.z = cvtpk(a1[0], a1[1]); w.w = cvtpk(a1[2], a1[3]);
;                     __builtin_nontemporal_store(w, (u32x4*)(rowp + bj * 32)); }
;                 asm volatile("" ::: "memory"); }
	v_add_f32_e32 v166, v166, v167
	ds_bpermute_b32 v167, v240, v166
	s_waitcnt lgkmcnt(0)
	v_add_f32_e32 v166, v166, v167
	v_fmamk_f32 v166, v166, 0x3c800000, v228
	v_cmp_gt_f32_e32 vcc, s52, v166
	v_mul_f32_e32 v167, 0x4b800000, v166
	s_nop 0
	v_cndmask_b32_e32 v166, v166, v167, vcc
	v_rsq_f32_e32 v166, v166
	s_nop 0
	v_mul_f32_e32 v167, 0x45800000, v166
	v_cndmask_b32_e32 v166, v166, v167, vcc
	v_mul_lo_u32 v167, s82, v171
	v_mul_lo_u32 v171, s83, v149
	v_add3_u32 v169, v169, v167, v171
	v_mul_f32_e32 v166, v170, v166
	v_lshl_add_u64 v[168:169], v[168:169], 1, s[84:85]
	v_lshl_add_u64 v[168:169], v[168:169], 0, s[48:49]
	v_pk_mul_f32 v[150:151], v[150:151], v[166:167] op_sel_hi:[1,0]
	v_pk_mul_f32 v[152:153], v[152:153], v[166:167] op_sel_hi:[1,0]
	v_pk_mul_f32 v[158:159], v[158:159], v[166:167] op_sel_hi:[1,0]
	v_pk_mul_f32 v[160:161], v[160:161], v[166:167] op_sel_hi:[1,0]
	v_lshl_add_u64 v[168:169], v[168:169], 0, s[28:29]
	v_pk_mul_f32 v[152:153], v[144:145], v[152:153]
	v_pk_mul_f32 v[150:151], v[142:143], v[150:151]
	v_pk_mul_f32 v[160:161], v[140:141], v[160:161]
	v_pk_mul_f32 v[158:159], v[138:139], v[158:159]
	v_lshl_add_u64 v[168:169], v[168:169], 0, v[0:1]
	v_cvt_pk_bf16_f32 v150, v150, v151
	v_cvt_pk_bf16_f32 v151, v152, v153
	v_cvt_pk_bf16_f32 v152, v158, v159
	v_cvt_pk_bf16_f32 v153, v160, v161
	flat_store_dwordx4 v[168:169], v[150:153] nt
	v_add_u32_e32 v149, 0x90, v148
	v_ashrrev_i32_e32 v171, 31, v149
	v_pk_mul_f32 v[150:151], v[156:157], v[166:167] op_sel_hi:[1,0]
	v_pk_mul_f32 v[152:153], v[154:155], v[166:167] op_sel_hi:[1,0]
	v_pk_mul_f32 v[154:155], v[164:165], v[166:167] op_sel_hi:[1,0]
	v_pk_mul_f32 v[156:157], v[162:163], v[166:167] op_sel_hi:[1,0]
	v_pk_mul_f32 v[152:153], v[136:137], v[152:153]
	v_pk_mul_f32 v[150:151], v[134:135], v[150:151]
	v_pk_mul_f32 v[156:157], v[132:133], v[156:157]
	v_pk_mul_f32 v[154:155], v[130:131], v[154:155]
	v_cvt_pk_bf16_f32 v150, v150, v151
	v_cvt_pk_bf16_f32 v151, v152, v153
	v_cvt_pk_bf16_f32 v152, v154, v155
	v_cvt_pk_bf16_f32 v153, v156, v157
	flat_store_dwordx4 v[168:169], v[150:153] offset:64 nt
	v_mov_b32_e32 v164, v181
	v_pk_mul_f32 v[160:161], v[44:45], v[164:165] op_sel_hi:[1,0]
	v_pk_mul_f32 v[150:151], v[46:47], v[164:165] op_sel_hi:[1,0]
	v_pk_mul_f32 v[152:153], v[48:49], v[164:165] op_sel_hi:[1,0]
	v_pk_mul_f32 v[156:157], v[150:151], v[150:151]
	v_pk_mul_f32 v[154:155], v[152:153], v[152:153]
	s_nop 0
	v_pk_mov_b32 v[158:159], v[156:157], v[154:155] op_sel:[1,0]
	v_mov_b32_e32 v157, v155
	v_pk_add_f32 v[154:155], v[158:159], v[156:157]
	v_pk_mul_f32 v[158:159], v[42:43], v[164:165] op_sel_hi:[1,0]
	v_pk_add_f32 v[166:167], v[154:155], v[154:155] op_sel_hi:[0,1]
	v_pk_mul_f32 v[154:155], v[160:161], v[160:161]
	v_pk_mul_f32 v[156:157], v[158:159], v[158:159]
	s_nop 0
	v_pk_mov_b32 v[162:163], v[156:157], v[154:155] op_sel:[1,0]
	v_mov_b32_e32 v157, v155
	v_pk_add_f32 v[154:155], v[162:163], v[156:157]
	v_pk_mul_f32 v[156:157], v[38:39], v[164:165] op_sel_hi:[1,0]
	v_pk_add_f32 v[168:169], v[154:155], v[154:155] op_sel_hi:[0,1]
	v_pk_mul_f32 v[154:155], v[40:41], v[164:165] op_sel_hi:[1,0]
	v_mul_f32_e32 v162, v156, v156
	v_pk_fma_f32 v[172:173], v[156:157], v[156:157], v[162:163] op_sel_hi:[1,1,0]
	v_mul_f32_e32 v162, v154, v154
	v_pk_fma_f32 v[174:175], v[154:155], v[154:155], v[162:163] op_sel_hi:[1,1,0]
	v_pk_mul_f32 v[162:163], v[36:37], v[164:165] op_sel_hi:[1,0]
	v_pk_mul_f32 v[164:165], v[34:35], v[164:165] op_sel_hi:[1,0]
	v_mul_f32_e32 v166, v162, v162
	v_mul_f32_e32 v172, v164, v164
	v_mul_f32_e32 v174, v165, v165
	v_mul_f32_e32 v168, v163, v163
	v_pk_add_f32 v[172:173], v[172:173], v[174:175]
	v_pk_add_f32 v[166:167], v[166:167], v[168:169]
	v_mad_u64_u32 v[168:169], s[2:3], s82, v149, 0
	v_pk_add_f32 v[166:167], v[172:173], v[166:167]
	s_nop 0
	v_add_f32_e32 v166, v166, v167
	ds_bpermute_b32 v167, v239, v166
	s_waitcnt lgkmcnt(0)
	v_add_f32_e32 v166, v166, v167
	ds_bpermute_b32 v167, v240, v166
	s_waitcnt lgkmcnt(0)
	v_add_f32_e32 v166, v166, v167
	v_fmamk_f32 v166, v166, 0x3c800000, v228
	v_cmp_gt_f32_e32 vcc, s52, v166
	v_mul_f32_e32 v167, 0x4b800000, v166
	s_nop 0
	v_cndmask_b32_e32 v166, v166, v167, vcc
	v_rsq_f32_e32 v166, v166
	s_nop 0
	v_mul_f32_e32 v167, 0x45800000, v166
	v_cndmask_b32_e32 v166, v166, v167, vcc
	v_mul_lo_u32 v167, s82, v171
	v_mul_lo_u32 v171, s83, v149
	v_add3_u32 v169, v169, v167, v171
	v_mul_f32_e32 v166, v170, v166
	v_lshl_add_u64 v[168:169], v[168:169], 1, s[84:85]
	v_lshl_add_u64 v[168:169], v[168:169], 0, s[48:49]
	v_pk_mul_f32 v[150:151], v[150:151], v[166:167] op_sel_hi:[1,0]
	v_pk_mul_f32 v[152:153], v[152:153], v[166:167] op_sel_hi:[1,0]
	v_pk_mul_f32 v[158:159], v[158:159], v[166:167] op_sel_hi:[1,0]
	v_pk_mul_f32 v[160:161], v[160:161], v[166:167] op_sel_hi:[1,0]
	v_lshl_add_u64 v[168:169], v[168:169], 0, s[28:29]
	v_pk_mul_f32 v[152:153], v[144:145], v[152:153]
	v_pk_mul_f32 v[150:151], v[142:143], v[150:151]
	v_pk_mul_f32 v[160:161], v[140:141], v[160:161]
	v_pk_mul_f32 v[158:159], v[138:139], v[158:159]
	v_lshl_add_u64 v[168:169], v[168:169], 0, v[0:1]
	v_cvt_pk_bf16_f32 v150, v150, v151
	v_cvt_pk_bf16_f32 v151, v152, v153
	v_cvt_pk_bf16_f32 v152, v158, v159
	v_cvt_pk_bf16_f32 v153, v160, v161
	flat_store_dwordx4 v[168:169], v[150:153] nt
	v_add_u32_e32 v149, 0xa0, v148
	v_ashrrev_i32_e32 v171, 31, v149
	v_pk_mul_f32 v[150:151], v[156:157], v[166:167] op_sel_hi:[1,0]
	v_pk_mul_f32 v[152:153], v[154:155], v[166:167] op_sel_hi:[1,0]
	v_pk_mul_f32 v[154:155], v[164:165], v[166:167] op_sel_hi:[1,0]
	v_pk_mul_f32 v[156:157], v[162:163], v[166:167] op_sel_hi:[1,0]
	v_pk_mul_f32 v[152:153], v[136:137], v[152:153]
; DI unsigned cvtpk(float lo, float hi) { f32x2_t v = {lo, hi}; bf16x2_t b = __builtin_convertvector(v, bf16x2_t); return __builtin_bit_cast(unsigned, b); }
; DI float shx(float v, int mask, int lane) { return __builtin_bit_cast(float, __builtin_amdgcn_ds_bpermute((lane ^ mask) << 2, __builtin_bit_cast(int, v))); }
;     DI void operator()(const f32x4 (&acc)[2][2][4][2], const Unit& u, int wr, int wc, int fr, int fq) const {
;     ...
;             for (int m = 0; m < 4; ++m) { const int row = row0 + ai * HALF + m * 16; const float sc = SS[row];
;                 f32x4 v[2][2]; float ss = 0.f;
; #pragma unroll
;                 for (int bj = 0; bj < 2; ++bj)
; #pragma unroll
;                     for (int n = 0; n < 2; ++n) { v[bj][n] = acc[ai][bj][m][n] * sc; ss += (v[bj][n][0] * v[bj][n][0] + v[bj][n][1] * v[bj][n][1]) + (v[bj][n][2] * v[bj][n][2] + v[bj][n][3] * v[bj][n][3]); }
;                 ss += shx(ss, 16, ln); ss += shx(ss, 32, ln);
;                 const float rs = rsqrtf(ss * (1.f / 64.f) + EPS) * ex;
;                 bf16_t* rowp = O + (size_t)row * ldc + u.pn * BM + wc * 64 + 8 * fq;
; #pragma unroll
;                 for (int bj = 0; bj < 2; ++bj) { const f32x4 a0 = v[bj][0] * rs * g[bj][0], a1 = v[bj][1] * rs * g[bj][1];
;                     u32x4 w; w.x = cvtpk(a0[0], a0[1]); w.y = cvtpk(a0[2], a0[3]); w.z = cvtpk(a1[0], a1[1]); w.w = cvtpk(a1[2], a1[3]);
;                     __builtin_nontemporal_store(w, (u32x4*)(rowp + bj * 32)); }
;                 asm volatile("" ::: "memory"); }
	v_pk_mul_f32 v[150:151], v[134:135], v[150:151]
	v_pk_mul_f32 v[156:157], v[132:133], v[156:157]
	v_pk_mul_f32 v[154:155], v[130:131], v[154:155]
	v_cvt_pk_bf16_f32 v150, v150, v151
	v_cvt_pk_bf16_f32 v151, v152, v153
	v_cvt_pk_bf16_f32 v152, v154, v155
	v_cvt_pk_bf16_f32 v153, v156, v157
	flat_store_dwordx4 v[168:169], v[150:153] offset:64 nt
	v_mov_b32_e32 v164, v182
	v_pk_mul_f32 v[160:161], v[28:29], v[164:165] op_sel_hi:[1,0]
	v_pk_mul_f32 v[150:151], v[30:31], v[164:165] op_sel_hi:[1,0]
	v_pk_mul_f32 v[152:153], v[32:33], v[164:165] op_sel_hi:[1,0]
	v_pk_mul_f32 v[156:157], v[150:151], v[150:151]
	v_pk_mul_f32 v[154:155], v[152:153], v[152:153]
	s_nop 0
	v_pk_mov_b32 v[158:159], v[156:157], v[154:155] op_sel:[1,0]
	v_mov_b32_e32 v157, v155
	v_pk_add_f32 v[154:155], v[158:159], v[156:157]
	v_pk_mul_f32 v[158:159], v[26:27], v[164:165] op_sel_hi:[1,0]
	v_pk_add_f32 v[166:167], v[154:155], v[154:155] op_sel_hi:[0,1]
	v_pk_mul_f32 v[154:155], v[160:161], v[160:161]
	v_pk_mul_f32 v[156:157], v[158:159], v[158:159]
	s_nop 0
	v_pk_mov_b32 v[162:163], v[156:157], v[154:155] op_sel:[1,0]
	v_mov_b32_e32 v157, v155
	v_pk_add_f32 v[154:155], v[162:163], v[156:157]
	v_pk_mul_f32 v[156:157], v[22:23], v[164:165] op_sel_hi:[1,0]
	v_pk_add_f32 v[168:169], v[154:155], v[154:155] op_sel_hi:[0,1]
	v_pk_mul_f32 v[154:155], v[24:25], v[164:165] op_sel_hi:[1,0]
	v_mul_f32_e32 v162, v156, v156
	v_pk_fma_f32 v[172:173], v[156:157], v[156:157], v[162:163] op_sel_hi:[1,1,0]
	v_mul_f32_e32 v162, v154, v154
	v_pk_fma_f32 v[174:175], v[154:155], v[154:155], v[162:163] op_sel_hi:[1,1,0]
	v_pk_mul_f32 v[162:163], v[20:21], v[164:165] op_sel_hi:[1,0]
	v_pk_mul_f32 v[164:165], v[18:19], v[164:165] op_sel_hi:[1,0]
	v_mul_f32_e32 v166, v162, v162
	v_mul_f32_e32 v172, v164, v164
	v_mul_f32_e32 v174, v165, v165
	v_mul_f32_e32 v168, v163, v163
	v_pk_add_f32 v[172:173], v[172:173], v[174:175]
	v_pk_add_f32 v[166:167], v[166:167], v[168:169]
	v_mad_u64_u32 v[168:169], s[2:3], s82, v149, 0
	v_pk_add_f32 v[166:167], v[172:173], v[166:167]
	s_nop 0
	v_add_f32_e32 v166, v166, v167
	ds_bpermute_b32 v167, v239, v166
	s_waitcnt lgkmcnt(0)
	v_add_f32_e32 v166, v166, v167
	ds_bpermute_b32 v167, v240, v166
	s_waitcnt lgkmcnt(0)
; DI unsigned cvtpk(float lo, float hi) { f32x2_t v = {lo, hi}; bf16x2_t b = __builtin_convertvector(v, bf16x2_t); return __builtin_bit_cast(unsigned, b); }
; DI float shx(float v, int mask, int lane) { return __builtin_bit_cast(float, __builtin_amdgcn_ds_bpermute((lane ^ mask) << 2, __builtin_bit_cast(int, v))); }
;     DI void operator()(const f32x4 (&acc)[2][2][4][2], const Unit& u, int wr, int wc, int fr, int fq) const {
;     ...
;             for (int m = 0; m < 4; ++m) { const int row = row0 + ai * HALF + m * 16; const float sc = SS[row];
;                 f32x4 v[2][2]; float ss = 0.f;
; #pragma unroll
;                 for (int bj = 0; bj < 2; ++bj)
; #pragma unroll
;                     for (int n = 0; n < 2; ++n) { v[bj][n] = acc[ai][bj][m][n] * sc; ss += (v[bj][n][0] * v[bj][n][0] + v[bj][n][1] * v[bj][n][1]) + (v[bj][n][2] * v[bj][n][2] + v[bj][n][3] * v[bj][n][3]); }
;                 ss += shx(ss, 16, ln); ss += shx(ss, 32, ln);
;                 const float rs = rsqrtf(ss * (1.f / 64.f) + EPS) * ex;
;                 bf16_t* rowp = O + (size_t)row * ldc + u.pn * BM + wc * 64 + 8 * fq;
; #pragma unroll
;                 for (int bj = 0; bj < 2; ++bj) { const f32x4 a0 = v[bj][0] * rs * g[bj][0], a1 = v[bj][1] * rs * g[bj][1];
;                     u32x4 w; w.x = cvtpk(a0[0], a0[1]); w.y = cvtpk(a0[2], a0[3]); w.z = cvtpk(a1[0], a1[1]); w.w = cvtpk(a1[2], a1[3]);
;                     __builtin_nontemporal_store(w, (u32x4*)(rowp + bj * 32)); }
;                 asm volatile("" ::: "memory"); }
	v_add_f32_e32 v166, v166, v167
	v_fmamk_f32 v166, v166, 0x3c800000, v228
	v_cmp_gt_f32_e32 vcc, s52, v166
	v_mul_f32_e32 v167, 0x4b800000, v166
	s_nop 0
	v_cndmask_b32_e32 v166, v166, v167, vcc
	v_rsq_f32_e32 v166, v166
	s_nop 0
	v_mul_f32_e32 v167, 0x45800000, v166
	v_cndmask_b32_e32 v166, v166, v167, vcc
	v_mul_lo_u32 v167, s82, v171
	v_mul_lo_u32 v171, s83, v149
	v_add3_u32 v169, v169, v167, v171
	v_mul_f32_e32 v166, v170, v166
	v_lshl_add_u64 v[168:169], v[168:169], 1, s[84:85]
	v_lshl_add_u64 v[168:169], v[168:169], 0, s[48:49]
	v_pk_mul_f32 v[150:151], v[150:151], v[166:167] op_sel_hi:[1,0]
	v_pk_mul_f32 v[152:153], v[152:153], v[166:167] op_sel_hi:[1,0]
	v_pk_mul_f32 v[158:159], v[158:159], v[166:167] op_sel_hi:[1,0]
	v_pk_mul_f32 v[160:161], v[160:161], v[166:167] op_sel_hi:[1,0]
	v_lshl_add_u64 v[168:169], v[168:169], 0, s[28:29]
	v_pk_mul_f32 v[152:153], v[144:145], v[152:153]
	v_pk_mul_f32 v[150:151], v[142:143], v[150:151]
	v_pk_mul_f32 v[160:161], v[140:141], v[160:161]
	v_pk_mul_f32 v[158:159], v[138:139], v[158:159]
	v_lshl_add_u64 v[168:169], v[168:169], 0, v[0:1]
	v_cvt_pk_bf16_f32 v150, v150, v151
	v_cvt_pk_bf16_f32 v151, v152, v153
	v_cvt_pk_bf16_f32 v152, v158, v159
	v_cvt_pk_bf16_f32 v153, v160, v161
	flat_store_dwordx4 v[168:169], v[150:153] nt
	v_add_u32_e32 v171, 0xb0, v148
	v_ashrrev_i32_e32 v172, 31, v171
	v_pk_mul_f32 v[150:151], v[156:157], v[166:167] op_sel_hi:[1,0]
	v_pk_mul_f32 v[152:153], v[154:155], v[166:167] op_sel_hi:[1,0]
	v_pk_mul_f32 v[154:155], v[164:165], v[166:167] op_sel_hi:[1,0]
	v_pk_mul_f32 v[156:157], v[162:163], v[166:167] op_sel_hi:[1,0]
	v_pk_mul_f32 v[152:153], v[136:137], v[152:153]
	v_pk_mul_f32 v[150:151], v[134:135], v[150:151]
	v_pk_mul_f32 v[156:157], v[132:133], v[156:157]
	v_pk_mul_f32 v[154:155], v[130:131], v[154:155]
	v_cvt_pk_bf16_f32 v150, v150, v151
	v_cvt_pk_bf16_f32 v151, v152, v153
	v_cvt_pk_bf16_f32 v152, v154, v155
	v_cvt_pk_bf16_f32 v153, v156, v157
	flat_store_dwordx4 v[168:169], v[150:153] offset:64 nt
	v_mov_b32_e32 v160, v183
	v_pk_mul_f32 v[146:147], v[14:15], v[160:161] op_sel_hi:[1,0]
	v_pk_mul_f32 v[148:149], v[16:17], v[160:161] op_sel_hi:[1,0]
	v_pk_mul_f32 v[152:153], v[146:147], v[146:147]
	v_pk_mul_f32 v[150:151], v[148:149], v[148:149]
	v_pk_mul_f32 v[156:157], v[12:13], v[160:161] op_sel_hi:[1,0]
	v_pk_mov_b32 v[154:155], v[152:153], v[150:151] op_sel:[1,0]
	v_mov_b32_e32 v153, v151
	v_pk_add_f32 v[150:151], v[154:155], v[152:153]
	v_pk_mul_f32 v[154:155], v[10:11], v[160:161] op_sel_hi:[1,0]
	v_pk_add_f32 v[162:163], v[150:151], v[150:151] op_sel_hi:[0,1]
	v_pk_mul_f32 v[150:151], v[156:157], v[156:157]
	v_pk_mul_f32 v[152:153], v[154:155], v[154:155]
	s_nop 0
	v_pk_mov_b32 v[158:159], v[152:153], v[150:151] op_sel:[1,0]
	v_mov_b32_e32 v153, v151
	v_pk_add_f32 v[150:151], v[158:159], v[152:153]
	v_pk_mul_f32 v[152:153], v[6:7], v[160:161] op_sel_hi:[1,0]
	v_pk_add_f32 v[164:165], v[150:151], v[150:151] op_sel_hi:[0,1]
	v_pk_mul_f32 v[150:151], v[8:9], v[160:161] op_sel_hi:[1,0]
	v_mul_f32_e32 v158, v152, v152
	v_pk_fma_f32 v[166:167], v[152:153], v[152:153], v[158:159] op_sel_hi:[1,1,0]
	v_mul_f32_e32 v158, v150, v150
	v_pk_fma_f32 v[168:169], v[150:151], v[150:151], v[158:159] op_sel_hi:[1,1,0]
	v_pk_mul_f32 v[158:159], v[4:5], v[160:161] op_sel_hi:[1,0]
	v_pk_mul_f32 v[160:161], v[2:3], v[160:161] op_sel_hi:[1,0]
	v_mul_f32_e32 v162, v158, v158
	v_mul_f32_e32 v166, v160, v160
	v_mul_f32_e32 v168, v161, v161
	v_mul_f32_e32 v164, v159, v159
	v_pk_add_f32 v[166:167], v[166:167], v[168:169]
	v_pk_add_f32 v[162:163], v[162:163], v[164:165]
	v_mad_u64_u32 v[164:165], s[2:3], s82, v171, 0
	v_pk_add_f32 v[162:163], v[166:167], v[162:163]
	v_mul_lo_u32 v166, s83, v171
	v_add_f32_e32 v162, v162, v163
	ds_bpermute_b32 v163, v239, v162
	s_waitcnt lgkmcnt(0)
	v_add_f32_e32 v162, v162, v163
	ds_bpermute_b32 v163, v240, v162
	s_waitcnt lgkmcnt(0)
	v_add_f32_e32 v162, v162, v163
	v_fmamk_f32 v162, v162, 0x3c800000, v228
	v_cmp_gt_f32_e32 vcc, s52, v162
	v_mul_f32_e32 v163, 0x4b800000, v162
	s_nop 0
	v_cndmask_b32_e32 v162, v162, v163, vcc
	v_rsq_f32_e32 v162, v162
	s_nop 0
	v_mul_f32_e32 v163, 0x45800000, v162
	v_cndmask_b32_e32 v162, v162, v163, vcc
	v_mul_lo_u32 v163, s82, v172
	v_mul_f32_e32 v162, v170, v162
	v_add3_u32 v165, v165, v163, v166
	v_lshl_add_u64 v[164:165], v[164:165], 1, s[84:85]
	v_pk_mul_f32 v[146:147], v[146:147], v[162:163] op_sel_hi:[1,0]
	v_pk_mul_f32 v[148:149], v[148:149], v[162:163] op_sel_hi:[1,0]
	v_lshl_add_u64 v[164:165], v[164:165], 0, s[48:49]
	v_pk_mul_f32 v[144:145], v[144:145], v[148:149]
	v_pk_mul_f32 v[142:143], v[142:143], v[146:147]
	v_pk_mul_f32 v[146:147], v[154:155], v[162:163] op_sel_hi:[1,0]
	v_pk_mul_f32 v[148:149], v[156:157], v[162:163] op_sel_hi:[1,0]
	v_lshl_add_u64 v[164:165], v[164:165], 0, s[28:29]
	v_pk_mul_f32 v[148:149], v[140:141], v[148:149]
	v_pk_mul_f32 v[140:141], v[138:139], v[146:147]
	v_lshl_add_u64 v[164:165], v[164:165], 0, v[0:1]
	v_cvt_pk_bf16_f32 v138, v142, v143
	v_cvt_pk_bf16_f32 v139, v144, v145
	v_cvt_pk_bf16_f32 v140, v140, v141
	v_cvt_pk_bf16_f32 v141, v148, v149
	flat_store_dwordx4 v[164:165], v[138:141] nt
	s_mov_b64 s[48:49], 0
	s_nop 0
	v_pk_mul_f32 v[138:139], v[152:153], v[162:163] op_sel_hi:[1,0]
	v_pk_mul_f32 v[140:141], v[150:151], v[162:163] op_sel_hi:[1,0]
	v_pk_mul_f32 v[134:135], v[134:135], v[138:139]
	v_pk_mul_f32 v[136:137], v[136:137], v[140:141]
	v_pk_mul_f32 v[138:139], v[160:161], v[162:163] op_sel_hi:[1,0]
	v_pk_mul_f32 v[140:141], v[158:159], v[162:163] op_sel_hi:[1,0]
	s_nop 0
	v_pk_mul_f32 v[140:141], v[132:133], v[140:141]
	v_pk_mul_f32 v[132:133], v[130:131], v[138:139]
	v_cvt_pk_bf16_f32 v130, v134, v135
	v_cvt_pk_bf16_f32 v131, v136, v137
	v_cvt_pk_bf16_f32 v132, v132, v133
	v_cvt_pk_bf16_f32 v133, v140, v141
	flat_store_dwordx4 v[164:165], v[130:133] offset:64 nt

; DI unsigned cvtpk(float lo, float hi) { f32x2_t v = {lo, hi}; bf16x2_t b = __builtin_convertvector(v, bf16x2_t); return __builtin_bit_cast(unsigned, b); }
;     DI void operator()(const f32x4 (&acc)[2][2][4][2], const Unit& u, int wr, int wc, int fr, int fq) const {
;     ...
;             for (int m = 0; m < 4; ++m) { const int row = row0 + ai * HALF + m * 16; float sc = 1.f; if (SS) { if (invn > 0.f) { const f32x4 q4 = *(const f32x4*)(SS + (size_t)row * 4); sc = rsqrtf(((q4.x + q4.y) + (q4.z + q4.w)) * invn + EPS); } else sc = SS[row]; }
;                 bf16_t* rowp = O + (size_t)row * ldc + col0;
; #pragma unroll
;                 for (int bj = 0; bj < 2; ++bj) { f32x4 v0 = acc[ai][bj][m][0] * sc, v1 = acc[ai][bj][m][1] * sc;
;                     if (ACT == 1) {
; #pragma unroll
;                         for (int e = 0; e < 4; ++e) { const float a = fmaxf(v0[e], 0.f), b = fmaxf(v1[e], 0.f); v0[e] = a * a; v1[e] = b * b; } }
;                     u32x4 w; w.x = cvtpk(v0[0], v0[1]); w.y = cvtpk(v0[2], v0[3]); w.z = cvtpk(v1[0], v1[1]); w.w = cvtpk(v1[2], v1[3]);
;                     if (ACT == 1) __builtin_nontemporal_store(w, (u32x4*)(rowp + bj * HALF));
;                     else *(u32x4*)(rowp + bj * HALF) = w; }
;                 asm volatile("" ::: "memory"); }
.LBB0_689:
	v_readlane_b32 s2, v253, 43
	v_readlane_b32 s3, v253, 44
	s_mov_b64 s[0:1], -1
	s_cmp_gt_i32 s24, 0
	v_cndmask_b32_e64 v0, 0, 1, s[2:3]
	s_waitcnt lgkmcnt(0)
	v_lshl_add_u32 v130, s64, 8, v237
	v_cmp_ne_u32_e64 s[48:49], 1, v0
	s_cbranch_scc0 .LBB0_731
	v_ashrrev_i32_e32 v131, 31, v130
	v_mov_b32_e32 v0, 1.0
	s_and_b64 vcc, exec, s[48:49]
	v_mov_b32_e32 v134, 1.0
	s_cbranch_vccnz .LBB0_695
	s_and_b64 vcc, exec, s[20:21]
	s_cbranch_vccz .LBB0_693
	v_lshl_add_u64 v[132:133], v[130:131], 2, s[86:87]
	global_load_dword v134, v[132:133], off
	global_load_dword v148, v[132:133], off offset:64
	global_load_dword v149, v[132:133], off offset:128
	global_load_dword v150, v[132:133], off offset:192
	global_load_dword v151, v[132:133], off offset:512
	global_load_dword v152, v[132:133], off offset:576
	global_load_dword v153, v[132:133], off offset:640
	global_load_dword v154, v[132:133], off offset:704
	s_mov_b64 s[0:1], 0

; DI unsigned cvtpk(float lo, float hi) { f32x2_t v = {lo, hi}; bf16x2_t b = __builtin_convertvector(v, bf16x2_t); return __builtin_bit_cast(unsigned, b); }
;     DI void operator()(const f32x4 (&acc)[2][2][4][2], const Unit& u, int wr, int wc, int fr, int fq) const {
;     ...
;             for (int m = 0; m < 4; ++m) { const int row = row0 + ai * HALF + m * 16; float sc = 1.f; if (SS) { if (invn > 0.f) { const f32x4 q4 = *(const f32x4*)(SS + (size_t)row * 4); sc = rsqrtf(((q4.x + q4.y) + (q4.z + q4.w)) * invn + EPS); } else sc = SS[row]; }
;                 bf16_t* rowp = O + (size_t)row * ldc + col0;
; #pragma unroll
;                 for (int bj = 0; bj < 2; ++bj) { f32x4 v0 = acc[ai][bj][m][0] * sc, v1 = acc[ai][bj][m][1] * sc;
;                     if (ACT == 1) {
; #pragma unroll
;                         for (int e = 0; e < 4; ++e) { const float a = fmaxf(v0[e], 0.f), b = fmaxf(v1[e], 0.f); v0[e] = a * a; v1[e] = b * b; } }
;                     u32x4 w; w.x = cvtpk(v0[0], v0[1]); w.y = cvtpk(v0[2], v0[3]); w.z = cvtpk(v1[0], v1[1]); w.w = cvtpk(v1[2], v1[3]);
;                     if (ACT == 1) __builtin_nontemporal_store(w, (u32x4*)(rowp + bj * HALF));
;                     else *(u32x4*)(rowp + bj * HALF) = w; }
;                 asm volatile("" ::: "memory"); }
.LBB0_695:
	v_mul_lo_u32 v135, s83, v130
	v_mul_lo_u32 v138, s82, v131
	v_mad_u64_u32 v[136:137], s[0:1], s82, v130, 0
	v_lshl_or_b32 v132, s65, 8, v244
	v_add3_u32 v137, v137, v138, v135
	v_ashrrev_i32_e32 v133, 31, v132
	v_lshl_add_u64 v[136:137], v[136:137], 1, s[84:85]
	v_lshl_add_u64 v[140:141], v[132:133], 1, v[136:137]
	s_waitcnt vmcnt(0) lgkmcnt(0)
	v_pk_mul_f32 v[136:137], v[128:129], v[134:135] op_sel_hi:[1,0]
	v_pk_mul_f32 v[138:139], v[126:127], v[134:135] op_sel_hi:[1,0]
	v_pk_mul_f32 v[142:143], v[124:125], v[134:135] op_sel_hi:[1,0]
	v_pk_mul_f32 v[144:145], v[122:123], v[134:135] op_sel_hi:[1,0]
	v_max_f32_e32 v138, 0, v138
	v_max_f32_e32 v144, 0, v144
	v_max_f32_e32 v139, 0, v139
	v_max_f32_e32 v145, 0, v145
	v_max_f32_e32 v136, 0, v136
	v_max_f32_e32 v142, 0, v142
	v_max_f32_e32 v137, 0, v137
	v_max_f32_e32 v143, 0, v143
	v_pk_mul_f32 v[138:139], v[138:139], v[138:139]
	v_pk_mul_f32 v[144:145], v[144:145], v[144:145]
	v_pk_mul_f32 v[146:147], v[136:137], v[136:137]
	v_pk_mul_f32 v[142:143], v[142:143], v[142:143]
	v_cvt_pk_bf16_f32 v136, v138, v139
	v_cvt_pk_bf16_f32 v137, v146, v147
	v_cvt_pk_bf16_f32 v138, v144, v145
	v_cvt_pk_bf16_f32 v139, v142, v143
	flat_store_dwordx4 v[140:141], v[136:139] nt
	v_pk_mul_f32 v[142:143], v[116:117], v[134:135] op_sel_hi:[1,0]
	s_and_b64 vcc, exec, s[48:49]
	v_pk_mul_f32 v[136:137], v[120:121], v[134:135] op_sel_hi:[1,0]
	v_pk_mul_f32 v[138:139], v[118:119], v[134:135] op_sel_hi:[1,0]
	v_pk_mul_f32 v[134:135], v[114:115], v[134:135] op_sel_hi:[1,0]
	v_max_f32_e32 v138, 0, v138
	v_max_f32_e32 v134, 0, v134
	v_max_f32_e32 v135, 0, v135
	v_max_f32_e32 v139, 0, v139
	v_pk_mul_f32 v[144:145], v[134:135], v[134:135]
	v_max_f32_e32 v134, 0, v136
	v_max_f32_e32 v136, 0, v142
	v_max_f32_e32 v135, 0, v137
	v_max_f32_e32 v137, 0, v143
	v_pk_mul_f32 v[138:139], v[138:139], v[138:139]
	v_pk_mul_f32 v[142:143], v[134:135], v[134:135]
	v_pk_mul_f32 v[146:147], v[136:137], v[136:137]
	v_cvt_pk_bf16_f32 v134, v138, v139
	v_cvt_pk_bf16_f32 v135, v142, v143
	v_cvt_pk_bf16_f32 v136, v144, v145
	v_cvt_pk_bf16_f32 v137, v146, v147
	flat_store_dwordx4 v[140:141], v[134:137] offset:256 nt
	s_nop 1
	v_or_b32_e32 v134, 16, v130
	v_ashrrev_i32_e32 v135, 31, v134
	s_cbranch_vccnz .LBB0_700
	s_andn2_b64 vcc, exec, s[20:21]
	s_mov_b64 s[0:1], -1
	s_cbranch_vccnz .LBB0_698
	v_lshl_add_u64 v[136:137], v[130:131], 2, s[86:87]
	v_mov_b32_e32 v0, v148
	s_mov_b64 s[0:1], 0

; DI unsigned cvtpk(float lo, float hi) { f32x2_t v = {lo, hi}; bf16x2_t b = __builtin_convertvector(v, bf16x2_t); return __builtin_bit_cast(unsigned, b); }
;     DI void operator()(const f32x4 (&acc)[2][2][4][2], const Unit& u, int wr, int wc, int fr, int fq) const {
;     ...
;             for (int m = 0; m < 4; ++m) { const int row = row0 + ai * HALF + m * 16; float sc = 1.f; if (SS) { if (invn > 0.f) { const f32x4 q4 = *(const f32x4*)(SS + (size_t)row * 4); sc = rsqrtf(((q4.x + q4.y) + (q4.z + q4.w)) * invn + EPS); } else sc = SS[row]; }
;                 bf16_t* rowp = O + (size_t)row * ldc + col0;
; #pragma unroll
;                 for (int bj = 0; bj < 2; ++bj) { f32x4 v0 = acc[ai][bj][m][0] * sc, v1 = acc[ai][bj][m][1] * sc;
;                     if (ACT == 1) {
; #pragma unroll
;                         for (int e = 0; e < 4; ++e) { const float a = fmaxf(v0[e], 0.f), b = fmaxf(v1[e], 0.f); v0[e] = a * a; v1[e] = b * b; } }
;                     u32x4 w; w.x = cvtpk(v0[0], v0[1]); w.y = cvtpk(v0[2], v0[3]); w.z = cvtpk(v1[0], v1[1]); w.w = cvtpk(v1[2], v1[3]);
;                     if (ACT == 1) __builtin_nontemporal_store(w, (u32x4*)(rowp + bj * HALF));
;                     else *(u32x4*)(rowp + bj * HALF) = w; }
;                 asm volatile("" ::: "memory"); }
.LBB0_700:
	v_mul_lo_u32 v136, s83, v134
	v_mul_lo_u32 v137, s82, v135
	v_mad_u64_u32 v[134:135], s[0:1], s82, v134, 0
	v_add3_u32 v135, v135, v137, v136
	v_lshl_add_u64 v[134:135], v[134:135], 1, s[84:85]
	v_lshl_add_u64 v[138:139], v[132:133], 1, v[134:135]
	v_pk_mul_f32 v[134:135], v[112:113], v[0:1] op_sel_hi:[1,0]
	v_pk_mul_f32 v[136:137], v[110:111], v[0:1] op_sel_hi:[1,0]
	v_pk_mul_f32 v[140:141], v[108:109], v[0:1] op_sel_hi:[1,0]
	v_pk_mul_f32 v[142:143], v[106:107], v[0:1] op_sel_hi:[1,0]
	v_max_f32_e32 v136, 0, v136
	v_max_f32_e32 v142, 0, v142
	v_max_f32_e32 v137, 0, v137
	v_max_f32_e32 v143, 0, v143
	v_max_f32_e32 v134, 0, v134
	v_max_f32_e32 v140, 0, v140
	v_max_f32_e32 v135, 0, v135
	v_max_f32_e32 v141, 0, v141
	v_pk_mul_f32 v[136:137], v[136:137], v[136:137]
	v_pk_mul_f32 v[142:143], v[142:143], v[142:143]
	v_pk_mul_f32 v[144:145], v[134:135], v[134:135]
	v_pk_mul_f32 v[140:141], v[140:141], v[140:141]
	v_cvt_pk_bf16_f32 v134, v136, v137
	v_cvt_pk_bf16_f32 v135, v144, v145
	v_cvt_pk_bf16_f32 v136, v142, v143
	v_cvt_pk_bf16_f32 v137, v140, v141
	flat_store_dwordx4 v[138:139], v[134:137] nt
	v_pk_mul_f32 v[140:141], v[100:101], v[0:1] op_sel_hi:[1,0]
	v_pk_mul_f32 v[142:143], v[98:99], v[0:1] op_sel_hi:[1,0]
	v_pk_mul_f32 v[134:135], v[104:105], v[0:1] op_sel_hi:[1,0]
	v_pk_mul_f32 v[136:137], v[102:103], v[0:1] op_sel_hi:[1,0]
	v_max_f32_e32 v142, 0, v142
	v_max_f32_e32 v136, 0, v136
	v_max_f32_e32 v137, 0, v137
	v_max_f32_e32 v143, 0, v143
	v_max_f32_e32 v134, 0, v134
	v_max_f32_e32 v140, 0, v140
	v_max_f32_e32 v135, 0, v135
	v_max_f32_e32 v141, 0, v141
	v_pk_mul_f32 v[136:137], v[136:137], v[136:137]
	v_pk_mul_f32 v[142:143], v[142:143], v[142:143]
	v_pk_mul_f32 v[144:145], v[134:135], v[134:135]
	v_pk_mul_f32 v[140:141], v[140:141], v[140:141]
	v_cvt_pk_bf16_f32 v134, v136, v137
	v_cvt_pk_bf16_f32 v135, v144, v145
	v_cvt_pk_bf16_f32 v136, v142, v143
	v_cvt_pk_bf16_f32 v137, v140, v141
	flat_store_dwordx4 v[138:139], v[134:137] offset:256 nt
	v_mov_b32_e32 v0, 1.0
	s_and_b64 vcc, exec, s[48:49]
	v_or_b32_e32 v136, 32, v130
	v_ashrrev_i32_e32 v137, 31, v136
	v_mov_b32_e32 v134, 1.0
	s_cbranch_vccnz .LBB0_705
	s_andn2_b64 vcc, exec, s[20:21]
	s_mov_b64 s[0:1], -1
	s_cbranch_vccnz .LBB0_703
	v_lshl_add_u64 v[134:135], v[130:131], 2, s[86:87]
	v_mov_b32_e32 v134, v149
	s_mov_b64 s[0:1], 0

; DI unsigned cvtpk(float lo, float hi) { f32x2_t v = {lo, hi}; bf16x2_t b = __builtin_convertvector(v, bf16x2_t); return __builtin_bit_cast(unsigned, b); }
;     DI void operator()(const f32x4 (&acc)[2][2][4][2], const Unit& u, int wr, int wc, int fr, int fq) const {
;     ...
;             for (int m = 0; m < 4; ++m) { const int row = row0 + ai * HALF + m * 16; float sc = 1.f; if (SS) { if (invn > 0.f) { const f32x4 q4 = *(const f32x4*)(SS + (size_t)row * 4); sc = rsqrtf(((q4.x + q4.y) + (q4.z + q4.w)) * invn + EPS); } else sc = SS[row]; }
;                 bf16_t* rowp = O + (size_t)row * ldc + col0;
; #pragma unroll
;                 for (int bj = 0; bj < 2; ++bj) { f32x4 v0 = acc[ai][bj][m][0] * sc, v1 = acc[ai][bj][m][1] * sc;
;                     if (ACT == 1) {
; #pragma unroll
;                         for (int e = 0; e < 4; ++e) { const float a = fmaxf(v0[e], 0.f), b = fmaxf(v1[e], 0.f); v0[e] = a * a; v1[e] = b * b; } }
;                     u32x4 w; w.x = cvtpk(v0[0], v0[1]); w.y = cvtpk(v0[2], v0[3]); w.z = cvtpk(v1[0], v1[1]); w.w = cvtpk(v1[2], v1[3]);
;                     if (ACT == 1) __builtin_nontemporal_store(w, (u32x4*)(rowp + bj * HALF));
;                     else *(u32x4*)(rowp + bj * HALF) = w; }
;                 asm volatile("" ::: "memory"); }
.LBB0_705:
	v_mul_lo_u32 v135, s83, v136
	v_mul_lo_u32 v138, s82, v137
	v_mad_u64_u32 v[136:137], s[0:1], s82, v136, 0
	v_add3_u32 v137, v137, v138, v135
	v_lshl_add_u64 v[136:137], v[136:137], 1, s[84:85]
	v_lshl_add_u64 v[140:141], v[132:133], 1, v[136:137]
	v_pk_mul_f32 v[136:137], v[96:97], v[134:135] op_sel_hi:[1,0]
	v_pk_mul_f32 v[138:139], v[94:95], v[134:135] op_sel_hi:[1,0]
	v_pk_mul_f32 v[142:143], v[92:93], v[134:135] op_sel_hi:[1,0]
	v_pk_mul_f32 v[144:145], v[90:91], v[134:135] op_sel_hi:[1,0]
	v_max_f32_e32 v138, 0, v138
	v_max_f32_e32 v144, 0, v144
	v_max_f32_e32 v139, 0, v139
	v_max_f32_e32 v145, 0, v145
	v_max_f32_e32 v136, 0, v136
	v_max_f32_e32 v142, 0, v142
	v_max_f32_e32 v137, 0, v137
	v_max_f32_e32 v143, 0, v143
	v_pk_mul_f32 v[138:139], v[138:139], v[138:139]
	v_pk_mul_f32 v[144:145], v[144:145], v[144:145]
	v_pk_mul_f32 v[146:147], v[136:137], v[136:137]
	v_pk_mul_f32 v[142:143], v[142:143], v[142:143]
	v_cvt_pk_bf16_f32 v136, v138, v139
	v_cvt_pk_bf16_f32 v137, v146, v147
	v_cvt_pk_bf16_f32 v138, v144, v145
	v_cvt_pk_bf16_f32 v139, v142, v143
	flat_store_dwordx4 v[140:141], v[136:139] nt
	v_pk_mul_f32 v[142:143], v[84:85], v[134:135] op_sel_hi:[1,0]
	s_and_b64 vcc, exec, s[48:49]
	v_pk_mul_f32 v[136:137], v[88:89], v[134:135] op_sel_hi:[1,0]
	v_pk_mul_f32 v[138:139], v[86:87], v[134:135] op_sel_hi:[1,0]
	v_pk_mul_f32 v[134:135], v[82:83], v[134:135] op_sel_hi:[1,0]
	v_max_f32_e32 v138, 0, v138
	v_max_f32_e32 v134, 0, v134
	v_max_f32_e32 v135, 0, v135
	v_max_f32_e32 v139, 0, v139
	v_pk_mul_f32 v[144:145], v[134:135], v[134:135]
	v_max_f32_e32 v134, 0, v136
	v_max_f32_e32 v136, 0, v142
	v_max_f32_e32 v135, 0, v137
	v_max_f32_e32 v137, 0, v143
	v_pk_mul_f32 v[138:139], v[138:139], v[138:139]
	v_pk_mul_f32 v[142:143], v[134:135], v[134:135]
	v_pk_mul_f32 v[146:147], v[136:137], v[136:137]
	v_cvt_pk_bf16_f32 v134, v138, v139
	v_cvt_pk_bf16_f32 v135, v142, v143
	v_cvt_pk_bf16_f32 v136, v144, v145
	v_cvt_pk_bf16_f32 v137, v146, v147
	flat_store_dwordx4 v[140:141], v[134:137] offset:256 nt
	s_nop 1
	v_or_b32_e32 v134, 48, v130
	v_ashrrev_i32_e32 v135, 31, v134
	s_cbranch_vccnz .LBB0_710
	s_andn2_b64 vcc, exec, s[20:21]
	s_mov_b64 s[0:1], -1
	s_cbranch_vccnz .LBB0_708
	v_lshl_add_u64 v[136:137], v[130:131], 2, s[86:87]
	v_mov_b32_e32 v0, v150
	s_mov_b64 s[0:1], 0

; DI unsigned cvtpk(float lo, float hi) { f32x2_t v = {lo, hi}; bf16x2_t b = __builtin_convertvector(v, bf16x2_t); return __builtin_bit_cast(unsigned, b); }
;     DI void operator()(const f32x4 (&acc)[2][2][4][2], const Unit& u, int wr, int wc, int fr, int fq) const {
;     ...
;             for (int m = 0; m < 4; ++m) { const int row = row0 + ai * HALF + m * 16; float sc = 1.f; if (SS) { if (invn > 0.f) { const f32x4 q4 = *(const f32x4*)(SS + (size_t)row * 4); sc = rsqrtf(((q4.x + q4.y) + (q4.z + q4.w)) * invn + EPS); } else sc = SS[row]; }
;                 bf16_t* rowp = O + (size_t)row * ldc + col0;
; #pragma unroll
;                 for (int bj = 0; bj < 2; ++bj) { f32x4 v0 = acc[ai][bj][m][0] * sc, v1 = acc[ai][bj][m][1] * sc;
;                     if (ACT == 1) {
; #pragma unroll
;                         for (int e = 0; e < 4; ++e) { const float a = fmaxf(v0[e], 0.f), b = fmaxf(v1[e], 0.f); v0[e] = a * a; v1[e] = b * b; } }
;                     u32x4 w; w.x = cvtpk(v0[0], v0[1]); w.y = cvtpk(v0[2], v0[3]); w.z = cvtpk(v1[0], v1[1]); w.w = cvtpk(v1[2], v1[3]);
;                     if (ACT == 1) __builtin_nontemporal_store(w, (u32x4*)(rowp + bj * HALF));
;                     else *(u32x4*)(rowp + bj * HALF) = w; }
;                 asm volatile("" ::: "memory"); }
.LBB0_710:
	v_mul_lo_u32 v136, s83, v134
	v_mul_lo_u32 v137, s82, v135
	v_mad_u64_u32 v[134:135], s[0:1], s82, v134, 0
	v_add3_u32 v135, v135, v137, v136
	v_lshl_add_u64 v[134:135], v[134:135], 1, s[84:85]
	v_lshl_add_u64 v[138:139], v[132:133], 1, v[134:135]
	v_pk_mul_f32 v[134:135], v[80:81], v[0:1] op_sel_hi:[1,0]
	v_pk_mul_f32 v[136:137], v[78:79], v[0:1] op_sel_hi:[1,0]
	v_pk_mul_f32 v[140:141], v[76:77], v[0:1] op_sel_hi:[1,0]
	v_pk_mul_f32 v[142:143], v[74:75], v[0:1] op_sel_hi:[1,0]
	v_max_f32_e32 v136, 0, v136
	v_max_f32_e32 v142, 0, v142
	v_max_f32_e32 v137, 0, v137
	v_max_f32_e32 v143, 0, v143
	v_max_f32_e32 v134, 0, v134
	v_max_f32_e32 v140, 0, v140
	v_max_f32_e32 v135, 0, v135
	v_max_f32_e32 v141, 0, v141
	v_pk_mul_f32 v[136:137], v[136:137], v[136:137]
	v_pk_mul_f32 v[142:143], v[142:143], v[142:143]
	v_pk_mul_f32 v[144:145], v[134:135], v[134:135]
	v_pk_mul_f32 v[140:141], v[140:141], v[140:141]
	v_cvt_pk_bf16_f32 v134, v136, v137
	v_cvt_pk_bf16_f32 v135, v144, v145
	v_cvt_pk_bf16_f32 v136, v142, v143
	v_cvt_pk_bf16_f32 v137, v140, v141
	flat_store_dwordx4 v[138:139], v[134:137] nt
	v_pk_mul_f32 v[140:141], v[68:69], v[0:1] op_sel_hi:[1,0]
	v_pk_mul_f32 v[142:143], v[66:67], v[0:1] op_sel_hi:[1,0]
	v_pk_mul_f32 v[134:135], v[72:73], v[0:1] op_sel_hi:[1,0]
	v_pk_mul_f32 v[136:137], v[70:71], v[0:1] op_sel_hi:[1,0]
	v_max_f32_e32 v142, 0, v142
	v_max_f32_e32 v136, 0, v136
	v_max_f32_e32 v137, 0, v137
	v_max_f32_e32 v143, 0, v143
	v_max_f32_e32 v134, 0, v134
	v_max_f32_e32 v140, 0, v140
	v_max_f32_e32 v135, 0, v135
	v_max_f32_e32 v141, 0, v141
	v_pk_mul_f32 v[136:137], v[136:137], v[136:137]
	v_pk_mul_f32 v[142:143], v[142:143], v[142:143]
	v_pk_mul_f32 v[144:145], v[134:135], v[134:135]
	v_pk_mul_f32 v[140:141], v[140:141], v[140:141]
	v_cvt_pk_bf16_f32 v134, v136, v137
	v_cvt_pk_bf16_f32 v135, v144, v145
	v_cvt_pk_bf16_f32 v136, v142, v143
	v_cvt_pk_bf16_f32 v137, v140, v141
	flat_store_dwordx4 v[138:139], v[134:137] offset:256 nt
	v_mov_b32_e32 v0, 1.0
	s_and_b64 vcc, exec, s[48:49]
	v_add_u32_e32 v136, 0x80, v130
	v_ashrrev_i32_e32 v137, 31, v136
	v_mov_b32_e32 v134, 1.0
	s_cbranch_vccnz .LBB0_715
	s_andn2_b64 vcc, exec, s[20:21]
	s_mov_b64 s[0:1], -1
	s_cbranch_vccnz .LBB0_713
	v_lshl_add_u64 v[134:135], v[130:131], 2, s[86:87]
	v_mov_b32_e32 v134, v151
	s_mov_b64 s[0:1], 0

; DI unsigned cvtpk(float lo, float hi) { f32x2_t v = {lo, hi}; bf16x2_t b = __builtin_convertvector(v, bf16x2_t); return __builtin_bit_cast(unsigned, b); }
;     DI void operator()(const f32x4 (&acc)[2][2][4][2], const Unit& u, int wr, int wc, int fr, int fq) const {
;     ...
;             for (int m = 0; m < 4; ++m) { const int row = row0 + ai * HALF + m * 16; float sc = 1.f; if (SS) { if (invn > 0.f) { const f32x4 q4 = *(const f32x4*)(SS + (size_t)row * 4); sc = rsqrtf(((q4.x + q4.y) + (q4.z + q4.w)) * invn + EPS); } else sc = SS[row]; }
;                 bf16_t* rowp = O + (size_t)row * ldc + col0;
; #pragma unroll
;                 for (int bj = 0; bj < 2; ++bj) { f32x4 v0 = acc[ai][bj][m][0] * sc, v1 = acc[ai][bj][m][1] * sc;
;                     if (ACT == 1) {
; #pragma unroll
;                         for (int e = 0; e < 4; ++e) { const float a = fmaxf(v0[e], 0.f), b = fmaxf(v1[e], 0.f); v0[e] = a * a; v1[e] = b * b; } }
;                     u32x4 w; w.x = cvtpk(v0[0], v0[1]); w.y = cvtpk(v0[2], v0[3]); w.z = cvtpk(v1[0], v1[1]); w.w = cvtpk(v1[2], v1[3]);
;                     if (ACT == 1) __builtin_nontemporal_store(w, (u32x4*)(rowp + bj * HALF));
;                     else *(u32x4*)(rowp + bj * HALF) = w; }
;                 asm volatile("" ::: "memory"); }
.LBB0_715:
	v_mul_lo_u32 v135, s83, v136
	v_mul_lo_u32 v138, s82, v137
	v_mad_u64_u32 v[136:137], s[0:1], s82, v136, 0
	v_add3_u32 v137, v137, v138, v135
	v_lshl_add_u64 v[136:137], v[136:137], 1, s[84:85]
	v_lshl_add_u64 v[140:141], v[132:133], 1, v[136:137]
	v_pk_mul_f32 v[136:137], v[64:65], v[134:135] op_sel_hi:[1,0]
	v_pk_mul_f32 v[138:139], v[62:63], v[134:135] op_sel_hi:[1,0]
	v_pk_mul_f32 v[142:143], v[60:61], v[134:135] op_sel_hi:[1,0]
	v_pk_mul_f32 v[144:145], v[58:59], v[134:135] op_sel_hi:[1,0]
	v_max_f32_e32 v138, 0, v138
	v_max_f32_e32 v144, 0, v144
	v_max_f32_e32 v139, 0, v139
	v_max_f32_e32 v145, 0, v145
	v_max_f32_e32 v136, 0, v136
	v_max_f32_e32 v142, 0, v142
	v_max_f32_e32 v137, 0, v137
	v_max_f32_e32 v143, 0, v143
	v_pk_mul_f32 v[138:139], v[138:139], v[138:139]
	v_pk_mul_f32 v[144:145], v[144:145], v[144:145]
	v_pk_mul_f32 v[146:147], v[136:137], v[136:137]
	v_pk_mul_f32 v[142:143], v[142:143], v[142:143]
	v_cvt_pk_bf16_f32 v136, v138, v139
	v_cvt_pk_bf16_f32 v137, v146, v147
	v_cvt_pk_bf16_f32 v138, v144, v145
	v_cvt_pk_bf16_f32 v139, v142, v143
	flat_store_dwordx4 v[140:141], v[136:139] nt
	v_pk_mul_f32 v[142:143], v[52:53], v[134:135] op_sel_hi:[1,0]
	s_and_b64 vcc, exec, s[48:49]
	v_pk_mul_f32 v[136:137], v[56:57], v[134:135] op_sel_hi:[1,0]
	v_pk_mul_f32 v[138:139], v[54:55], v[134:135] op_sel_hi:[1,0]
	v_pk_mul_f32 v[134:135], v[50:51], v[134:135] op_sel_hi:[1,0]
	v_max_f32_e32 v138, 0, v138
	v_max_f32_e32 v134, 0, v134
	v_max_f32_e32 v135, 0, v135
	v_max_f32_e32 v139, 0, v139
	v_pk_mul_f32 v[144:145], v[134:135], v[134:135]
	v_max_f32_e32 v134, 0, v136
	v_max_f32_e32 v136, 0, v142
	v_max_f32_e32 v135, 0, v137
	v_max_f32_e32 v137, 0, v143
	v_pk_mul_f32 v[138:139], v[138:139], v[138:139]
	v_pk_mul_f32 v[142:143], v[134:135], v[134:135]
	v_pk_mul_f32 v[146:147], v[136:137], v[136:137]
	v_cvt_pk_bf16_f32 v134, v138, v139
	v_cvt_pk_bf16_f32 v135, v142, v143
	v_cvt_pk_bf16_f32 v136, v144, v145
	v_cvt_pk_bf16_f32 v137, v146, v147
	flat_store_dwordx4 v[140:141], v[134:137] offset:256 nt
	s_nop 1
	v_add_u32_e32 v134, 0x90, v130
	v_ashrrev_i32_e32 v135, 31, v134
	s_cbranch_vccnz .LBB0_720
	s_andn2_b64 vcc, exec, s[20:21]
	s_mov_b64 s[0:1], -1
	s_cbranch_vccnz .LBB0_718
	v_lshl_add_u64 v[136:137], v[130:131], 2, s[86:87]
	v_mov_b32_e32 v0, v152
	s_mov_b64 s[0:1], 0

; DI unsigned cvtpk(float lo, float hi) { f32x2_t v = {lo, hi}; bf16x2_t b = __builtin_convertvector(v, bf16x2_t); return __builtin_bit_cast(unsigned, b); }
;     DI void operator()(const f32x4 (&acc)[2][2][4][2], const Unit& u, int wr, int wc, int fr, int fq) const {
;     ...
;             for (int m = 0; m < 4; ++m) { const int row = row0 + ai * HALF + m * 16; float sc = 1.f; if (SS) { if (invn > 0.f) { const f32x4 q4 = *(const f32x4*)(SS + (size_t)row * 4); sc = rsqrtf(((q4.x + q4.y) + (q4.z + q4.w)) * invn + EPS); } else sc = SS[row]; }
;                 bf16_t* rowp = O + (size_t)row * ldc + col0;
; #pragma unroll
;                 for (int bj = 0; bj < 2; ++bj) { f32x4 v0 = acc[ai][bj][m][0] * sc, v1 = acc[ai][bj][m][1] * sc;
;                     if (ACT == 1) {
; #pragma unroll
;                         for (int e = 0; e < 4; ++e) { const float a = fmaxf(v0[e], 0.f), b = fmaxf(v1[e], 0.f); v0[e] = a * a; v1[e] = b * b; } }
;                     u32x4 w; w.x = cvtpk(v0[0], v0[1]); w.y = cvtpk(v0[2], v0[3]); w.z = cvtpk(v1[0], v1[1]); w.w = cvtpk(v1[2], v1[3]);
;                     if (ACT == 1) __builtin_nontemporal_store(w, (u32x4*)(rowp + bj * HALF));
;                     else *(u32x4*)(rowp + bj * HALF) = w; }
;                 asm volatile("" ::: "memory"); }
.LBB0_720:
	v_mul_lo_u32 v136, s83, v134
	v_mul_lo_u32 v137, s82, v135
	v_mad_u64_u32 v[134:135], s[0:1], s82, v134, 0
	v_add3_u32 v135, v135, v137, v136
	v_lshl_add_u64 v[134:135], v[134:135], 1, s[84:85]
	v_lshl_add_u64 v[138:139], v[132:133], 1, v[134:135]
	v_pk_mul_f32 v[134:135], v[48:49], v[0:1] op_sel_hi:[1,0]
	v_pk_mul_f32 v[136:137], v[46:47], v[0:1] op_sel_hi:[1,0]
	v_pk_mul_f32 v[140:141], v[44:45], v[0:1] op_sel_hi:[1,0]
	v_pk_mul_f32 v[142:143], v[42:43], v[0:1] op_sel_hi:[1,0]
	v_max_f32_e32 v136, 0, v136
	v_max_f32_e32 v142, 0, v142
	v_max_f32_e32 v137, 0, v137
	v_max_f32_e32 v143, 0, v143
	v_max_f32_e32 v134, 0, v134
	v_max_f32_e32 v140, 0, v140
	v_max_f32_e32 v135, 0, v135
	v_max_f32_e32 v141, 0, v141
	v_pk_mul_f32 v[136:137], v[136:137], v[136:137]
	v_pk_mul_f32 v[142:143], v[142:143], v[142:143]
	v_pk_mul_f32 v[144:145], v[134:135], v[134:135]
	v_pk_mul_f32 v[140:141], v[140:141], v[140:141]
	v_cvt_pk_bf16_f32 v134, v136, v137
	v_cvt_pk_bf16_f32 v135, v144, v145
	v_cvt_pk_bf16_f32 v136, v142, v143
	v_cvt_pk_bf16_f32 v137, v140, v141
	flat_store_dwordx4 v[138:139], v[134:137] nt
	v_pk_mul_f32 v[140:141], v[36:37], v[0:1] op_sel_hi:[1,0]
	v_pk_mul_f32 v[142:143], v[34:35], v[0:1] op_sel_hi:[1,0]
	v_pk_mul_f32 v[134:135], v[40:41], v[0:1] op_sel_hi:[1,0]
	v_pk_mul_f32 v[136:137], v[38:39], v[0:1] op_sel_hi:[1,0]
	v_max_f32_e32 v142, 0, v142
	v_max_f32_e32 v136, 0, v136
	v_max_f32_e32 v137, 0, v137
	v_max_f32_e32 v143, 0, v143
	v_max_f32_e32 v134, 0, v134
	v_max_f32_e32 v140, 0, v140
	v_max_f32_e32 v135, 0, v135
	v_max_f32_e32 v141, 0, v141
	v_pk_mul_f32 v[136:137], v[136:137], v[136:137]
	v_pk_mul_f32 v[142:143], v[142:143], v[142:143]
	v_pk_mul_f32 v[144:145], v[134:135], v[134:135]
	v_pk_mul_f32 v[140:141], v[140:141], v[140:141]
	v_cvt_pk_bf16_f32 v134, v136, v137
	v_cvt_pk_bf16_f32 v135, v144, v145
	v_cvt_pk_bf16_f32 v136, v142, v143
	v_cvt_pk_bf16_f32 v137, v140, v141
	flat_store_dwordx4 v[138:139], v[134:137] offset:256 nt
	v_mov_b32_e32 v0, 1.0
	s_and_b64 vcc, exec, s[48:49]
	v_add_u32_e32 v136, 0xa0, v130
	v_ashrrev_i32_e32 v137, 31, v136
	v_mov_b32_e32 v134, 1.0
	s_cbranch_vccnz .LBB0_725
	s_andn2_b64 vcc, exec, s[20:21]
	s_mov_b64 s[0:1], -1
	s_cbranch_vccnz .LBB0_723
	v_lshl_add_u64 v[134:135], v[130:131], 2, s[86:87]
	v_mov_b32_e32 v134, v153
	s_mov_b64 s[0:1], 0

; DI unsigned cvtpk(float lo, float hi) { f32x2_t v = {lo, hi}; bf16x2_t b = __builtin_convertvector(v, bf16x2_t); return __builtin_bit_cast(unsigned, b); }
;     DI void operator()(const f32x4 (&acc)[2][2][4][2], const Unit& u, int wr, int wc, int fr, int fq) const {
;     ...
;             for (int m = 0; m < 4; ++m) { const int row = row0 + ai * HALF + m * 16; float sc = 1.f; if (SS) { if (invn > 0.f) { const f32x4 q4 = *(const f32x4*)(SS + (size_t)row * 4); sc = rsqrtf(((q4.x + q4.y) + (q4.z + q4.w)) * invn + EPS); } else sc = SS[row]; }
;                 bf16_t* rowp = O + (size_t)row * ldc + col0;
; #pragma unroll
;                 for (int bj = 0; bj < 2; ++bj) { f32x4 v0 = acc[ai][bj][m][0] * sc, v1 = acc[ai][bj][m][1] * sc;
;                     if (ACT == 1) {
; #pragma unroll
;                         for (int e = 0; e < 4; ++e) { const float a = fmaxf(v0[e], 0.f), b = fmaxf(v1[e], 0.f); v0[e] = a * a; v1[e] = b * b; } }
;                     u32x4 w; w.x = cvtpk(v0[0], v0[1]); w.y = cvtpk(v0[2], v0[3]); w.z = cvtpk(v1[0], v1[1]); w.w = cvtpk(v1[2], v1[3]);
;                     if (ACT == 1) __builtin_nontemporal_store(w, (u32x4*)(rowp + bj * HALF));
;                     else *(u32x4*)(rowp + bj * HALF) = w; }
;                 asm volatile("" ::: "memory"); }
.LBB0_725:
	v_mul_lo_u32 v135, s83, v136
	v_mul_lo_u32 v138, s82, v137
	v_mad_u64_u32 v[136:137], s[0:1], s82, v136, 0
	v_add3_u32 v137, v137, v138, v135
	v_lshl_add_u64 v[136:137], v[136:137], 1, s[84:85]
	v_lshl_add_u64 v[140:141], v[132:133], 1, v[136:137]
	v_pk_mul_f32 v[136:137], v[32:33], v[134:135] op_sel_hi:[1,0]
	v_pk_mul_f32 v[138:139], v[30:31], v[134:135] op_sel_hi:[1,0]
	v_pk_mul_f32 v[142:143], v[28:29], v[134:135] op_sel_hi:[1,0]
	v_pk_mul_f32 v[144:145], v[26:27], v[134:135] op_sel_hi:[1,0]
	v_max_f32_e32 v138, 0, v138
	v_max_f32_e32 v144, 0, v144
	v_max_f32_e32 v139, 0, v139
	v_max_f32_e32 v145, 0, v145
	v_max_f32_e32 v136, 0, v136
	v_max_f32_e32 v142, 0, v142
	v_max_f32_e32 v137, 0, v137
	v_max_f32_e32 v143, 0, v143
	v_pk_mul_f32 v[138:139], v[138:139], v[138:139]
	v_pk_mul_f32 v[144:145], v[144:145], v[144:145]
	v_pk_mul_f32 v[146:147], v[136:137], v[136:137]
	v_pk_mul_f32 v[142:143], v[142:143], v[142:143]
	v_cvt_pk_bf16_f32 v136, v138, v139
	v_cvt_pk_bf16_f32 v137, v146, v147
	v_cvt_pk_bf16_f32 v138, v144, v145
	v_cvt_pk_bf16_f32 v139, v142, v143
	flat_store_dwordx4 v[140:141], v[136:139] nt
	v_pk_mul_f32 v[142:143], v[20:21], v[134:135] op_sel_hi:[1,0]
	s_and_b64 vcc, exec, s[48:49]
	v_pk_mul_f32 v[136:137], v[24:25], v[134:135] op_sel_hi:[1,0]
	v_pk_mul_f32 v[138:139], v[22:23], v[134:135] op_sel_hi:[1,0]
	v_pk_mul_f32 v[134:135], v[18:19], v[134:135] op_sel_hi:[1,0]
	v_max_f32_e32 v138, 0, v138
	v_max_f32_e32 v134, 0, v134
	v_max_f32_e32 v135, 0, v135
	v_max_f32_e32 v139, 0, v139
	v_pk_mul_f32 v[144:145], v[134:135], v[134:135]
	v_max_f32_e32 v134, 0, v136
	v_max_f32_e32 v136, 0, v142
	v_max_f32_e32 v135, 0, v137
	v_max_f32_e32 v137, 0, v143
	v_pk_mul_f32 v[138:139], v[138:139], v[138:139]
	v_pk_mul_f32 v[142:143], v[134:135], v[134:135]
	v_pk_mul_f32 v[146:147], v[136:137], v[136:137]
	v_cvt_pk_bf16_f32 v134, v138, v139
	v_cvt_pk_bf16_f32 v135, v142, v143
	v_cvt_pk_bf16_f32 v136, v144, v145
	v_cvt_pk_bf16_f32 v137, v146, v147
	flat_store_dwordx4 v[140:141], v[134:137] offset:256 nt
	s_nop 1
	v_add_u32_e32 v134, 0xb0, v130
	v_ashrrev_i32_e32 v135, 31, v134
	s_cbranch_vccnz .LBB0_730
	s_andn2_b64 vcc, exec, s[20:21]
	s_mov_b64 s[0:1], -1
	s_cbranch_vccnz .LBB0_728
	v_lshl_add_u64 v[136:137], v[130:131], 2, s[86:87]
	v_mov_b32_e32 v0, v154
	s_mov_b64 s[0:1], 0

; DI unsigned cvtpk(float lo, float hi) { f32x2_t v = {lo, hi}; bf16x2_t b = __builtin_convertvector(v, bf16x2_t); return __builtin_bit_cast(unsigned, b); }
;     DI void operator()(const f32x4 (&acc)[2][2][4][2], const Unit& u, int wr, int wc, int fr, int fq) const {
;     ...
;             for (int m = 0; m < 4; ++m) { const int row = row0 + ai * HALF + m * 16; float sc = 1.f; if (SS) { if (invn > 0.f) { const f32x4 q4 = *(const f32x4*)(SS + (size_t)row * 4); sc = rsqrtf(((q4.x + q4.y) + (q4.z + q4.w)) * invn + EPS); } else sc = SS[row]; }
;                 bf16_t* rowp = O + (size_t)row * ldc + col0;
; #pragma unroll
;                 for (int bj = 0; bj < 2; ++bj) { f32x4 v0 = acc[ai][bj][m][0] * sc, v1 = acc[ai][bj][m][1] * sc;
;                     if (ACT == 1) {
; #pragma unroll
;                         for (int e = 0; e < 4; ++e) { const float a = fmaxf(v0[e], 0.f), b = fmaxf(v1[e], 0.f); v0[e] = a * a; v1[e] = b * b; } }
;                     u32x4 w; w.x = cvtpk(v0[0], v0[1]); w.y = cvtpk(v0[2], v0[3]); w.z = cvtpk(v1[0], v1[1]); w.w = cvtpk(v1[2], v1[3]);
;                     if (ACT == 1) __builtin_nontemporal_store(w, (u32x4*)(rowp + bj * HALF));
;                     else *(u32x4*)(rowp + bj * HALF) = w; }
;                 asm volatile("" ::: "memory"); }
.LBB0_730:
	v_mul_lo_u32 v131, s83, v134
	v_mul_lo_u32 v136, s82, v135
	v_mad_u64_u32 v[134:135], s[0:1], s82, v134, 0
	v_add3_u32 v135, v135, v136, v131
	v_lshl_add_u64 v[134:135], v[134:135], 1, s[84:85]
	v_lshl_add_u64 v[136:137], v[132:133], 1, v[134:135]
	v_pk_mul_f32 v[132:133], v[16:17], v[0:1] op_sel_hi:[1,0]
	v_pk_mul_f32 v[134:135], v[14:15], v[0:1] op_sel_hi:[1,0]
	v_pk_mul_f32 v[138:139], v[12:13], v[0:1] op_sel_hi:[1,0]
	v_pk_mul_f32 v[140:141], v[10:11], v[0:1] op_sel_hi:[1,0]
	v_max_f32_e32 v134, 0, v134
	v_max_f32_e32 v140, 0, v140
	v_max_f32_e32 v135, 0, v135
	v_max_f32_e32 v141, 0, v141
	v_max_f32_e32 v132, 0, v132
	v_max_f32_e32 v138, 0, v138
	v_max_f32_e32 v133, 0, v133
	v_max_f32_e32 v139, 0, v139
	v_pk_mul_f32 v[134:135], v[134:135], v[134:135]
	v_pk_mul_f32 v[140:141], v[140:141], v[140:141]
	v_pk_mul_f32 v[142:143], v[132:133], v[132:133]
	v_pk_mul_f32 v[138:139], v[138:139], v[138:139]
	v_cvt_pk_bf16_f32 v132, v134, v135
	v_cvt_pk_bf16_f32 v133, v142, v143
	v_cvt_pk_bf16_f32 v134, v140, v141
	v_cvt_pk_bf16_f32 v135, v138, v139
	flat_store_dwordx4 v[136:137], v[132:135] nt
	v_pk_mul_f32 v[138:139], v[4:5], v[0:1] op_sel_hi:[1,0]
	v_pk_mul_f32 v[140:141], v[2:3], v[0:1] op_sel_hi:[1,0]
	v_pk_mul_f32 v[132:133], v[8:9], v[0:1] op_sel_hi:[1,0]
	v_pk_mul_f32 v[134:135], v[6:7], v[0:1] op_sel_hi:[1,0]
	v_max_f32_e32 v140, 0, v140
	v_max_f32_e32 v134, 0, v134
	v_max_f32_e32 v135, 0, v135
	v_max_f32_e32 v141, 0, v141
	v_max_f32_e32 v132, 0, v132
	v_max_f32_e32 v138, 0, v138
	v_max_f32_e32 v133, 0, v133
	v_max_f32_e32 v139, 0, v139
	v_pk_mul_f32 v[134:135], v[134:135], v[134:135]
	v_pk_mul_f32 v[140:141], v[140:141], v[140:141]
	v_pk_mul_f32 v[142:143], v[132:133], v[132:133]
	v_pk_mul_f32 v[138:139], v[138:139], v[138:139]
	v_cvt_pk_bf16_f32 v132, v134, v135
	v_cvt_pk_bf16_f32 v133, v142, v143
	v_cvt_pk_bf16_f32 v134, v140, v141
	v_cvt_pk_bf16_f32 v135, v138, v139
	flat_store_dwordx4 v[136:137], v[132:135] offset:256 nt
	s_mov_b64 s[0:1], 0
